# phase 3 epilogue: merge-gate branch rewritten with packed f32 + saddr stores; head-tile sum-of-squares reductions via v_permlane16/32_swap instead of ds_bpermute
# speedup vs baseline: 1.0051x; 1.0051x over previous
; DI float fast_exp2(float x) { return __builtin_amdgcn_exp2f(x); }
; DI float fast_rcp(float x) { return __builtin_amdgcn_rcpf(x); }
;     DI void operator()(Acc& acc, const pg8::Unit& u, int wr, int wc, int fr, int fq, const Pre& pr) const {
;     ...
;             const int col = (pn - 11) * 128 + wc * 32 + fq * 8;
; #pragma unroll
;             for (int ai = 0; ai < 2; ++ai)
; #pragma unroll
;                 for (int m = 0; m < 4; ++m) {
;                     const int row = u.pm * 256 + ai * 128 + wr * 64 + m * 16 + fr;
;                     const float nrl = -1.4426950408889634f * __builtin_amdgcn_rsqf(msq_of(pr.v[ai * 4 + m]));
;                     f32x4 rr[2], gc[2];
; #pragma unroll
;                     for (int n = 0; n < 2; ++n)
; #pragma unroll
;                         for (int i = 0; i < 4; ++i) {
;                             const float da = 1.0f + fast_exp2(acc[ai][0][m][n][i] * nrl), dc = 1.0f + fminf(fast_exp2(acc[ai][1][m][n][i] * nrl), 1e18f);
;                             rr[n][i] = dc * fast_rcp(da); gc[n][i] = fast_rcp(dc);
;                         }
;                     store8(MG + (size_t)row * 2048 + col, rr[0], rr[1]);
;                     store8(MG + (size_t)row * 2048 + 1024 + col, gc[0], gc[1]);
;                 }
.LBB0_393:
	s_andn2_b64 vcc, exec, s[10:11]
	s_cbranch_vccnz .LBB0_395
	s_waitcnt vmcnt(0)
	v_fmamk_f32 v207, v174, 0x3a800000, v187
	v_rsq_f32_e32 v207, v207
	v_lshl_add_u32 v210, s12, 7, v182
	v_lshlrev_b32_e32 v210, 1, v210
	v_lshl_add_u32 v198, v170, 12, v210
	v_mul_f32_e32 v206, 0xbfb8aa3b, v207
	v_fmamk_f32 v209, v197, 0x3a800000, v187
	v_rsq_f32_e32 v209, v209
	v_add_u32_e32 v199, 0x10000, v198
	v_add_u32_e32 v200, 0x20000, v198
	v_add_u32_e32 v201, 0x30000, v198
	v_add_u32_e32 v202, 0x80000, v198
	v_add_u32_e32 v203, 0x90000, v198
	v_add_u32_e32 v204, 0xa0000, v198
	v_add_u32_e32 v205, 0xb0000, v198
	v_mul_f32_e32 v208, 0xbfb8aa3b, v209
	v_pk_mul_f32 v[126:127], v[126:127], v[206:207] op_sel_hi:[1,0]
	v_pk_mul_f32 v[128:129], v[128:129], v[206:207] op_sel_hi:[1,0]
	v_pk_mul_f32 v[122:123], v[122:123], v[206:207] op_sel_hi:[1,0]
	v_pk_mul_f32 v[124:125], v[124:125], v[206:207] op_sel_hi:[1,0]
	v_pk_mul_f32 v[118:119], v[118:119], v[206:207] op_sel_hi:[1,0]
	v_pk_mul_f32 v[120:121], v[120:121], v[206:207] op_sel_hi:[1,0]
	v_pk_mul_f32 v[114:115], v[114:115], v[206:207] op_sel_hi:[1,0]
	v_pk_mul_f32 v[116:117], v[116:117], v[206:207] op_sel_hi:[1,0]
	v_exp_f32_e32 v126, v126
	v_exp_f32_e32 v127, v127
	v_exp_f32_e32 v128, v128
	v_exp_f32_e32 v129, v129
	v_exp_f32_e32 v122, v122
	v_exp_f32_e32 v123, v123
	v_exp_f32_e32 v124, v124
	v_exp_f32_e32 v125, v125
	v_exp_f32_e32 v118, v118
	v_exp_f32_e32 v119, v119
	v_exp_f32_e32 v120, v120
	v_exp_f32_e32 v121, v121
	v_exp_f32_e32 v114, v114
	v_exp_f32_e32 v115, v115
	v_exp_f32_e32 v116, v116
	v_exp_f32_e32 v117, v117
	v_fmamk_f32 v207, v196, 0x3a800000, v187
	v_rsq_f32_e32 v207, v207
	v_pk_add_f32 v[126:127], v[126:127], 1.0 op_sel_hi:[1,0]
	v_pk_add_f32 v[128:129], v[128:129], 1.0 op_sel_hi:[1,0]
	v_pk_add_f32 v[122:123], v[122:123], 1.0 op_sel_hi:[1,0]
	v_pk_add_f32 v[124:125], v[124:125], 1.0 op_sel_hi:[1,0]
	v_min_f32_e32 v118, 0x5d5e0b6b, v118
	v_min_f32_e32 v119, 0x5d5e0b6b, v119
	v_min_f32_e32 v120, 0x5d5e0b6b, v120
	v_min_f32_e32 v121, 0x5d5e0b6b, v121
	v_min_f32_e32 v114, 0x5d5e0b6b, v114
	v_min_f32_e32 v115, 0x5d5e0b6b, v115
	v_min_f32_e32 v116, 0x5d5e0b6b, v116
	v_min_f32_e32 v117, 0x5d5e0b6b, v117
	v_rcp_f32_e32 v126, v126
	v_rcp_f32_e32 v127, v127
	v_rcp_f32_e32 v128, v128
	v_rcp_f32_e32 v129, v129
	v_rcp_f32_e32 v122, v122
	v_rcp_f32_e32 v123, v123
	v_rcp_f32_e32 v124, v124
	v_rcp_f32_e32 v125, v125
	v_pk_add_f32 v[118:119], v[118:119], 1.0 op_sel_hi:[1,0]
	v_pk_add_f32 v[120:121], v[120:121], 1.0 op_sel_hi:[1,0]
	v_pk_add_f32 v[114:115], v[114:115], 1.0 op_sel_hi:[1,0]
	v_pk_add_f32 v[116:117], v[116:117], 1.0 op_sel_hi:[1,0]
	v_mul_f32_e32 v206, 0xbfb8aa3b, v207
	v_pk_mul_f32 v[126:127], v[126:127], v[118:119]
	v_pk_mul_f32 v[128:129], v[128:129], v[120:121]
	v_pk_mul_f32 v[122:123], v[122:123], v[114:115]
	v_pk_mul_f32 v[124:125], v[124:125], v[116:117]
	v_rcp_f32_e32 v118, v118
	v_rcp_f32_e32 v119, v119
	v_rcp_f32_e32 v120, v120
	v_rcp_f32_e32 v121, v121
	v_rcp_f32_e32 v114, v114
	v_rcp_f32_e32 v115, v115
	v_rcp_f32_e32 v116, v116
	v_rcp_f32_e32 v117, v117
	v_cvt_pk_bf16_f32 v126, v126, v127
	v_cvt_pk_bf16_f32 v127, v128, v129
	v_cvt_pk_bf16_f32 v128, v122, v123
	v_cvt_pk_bf16_f32 v129, v124, v125
	global_store_dwordx4 v198, v[126:129], s[48:49]
	v_cvt_pk_bf16_f32 v118, v118, v119
	v_cvt_pk_bf16_f32 v119, v120, v121
	v_cvt_pk_bf16_f32 v120, v114, v115
	v_cvt_pk_bf16_f32 v121, v116, v117
	global_store_dwordx4 v198, v[118:121], s[48:49] offset:2048
	v_pk_mul_f32 v[110:111], v[110:111], v[208:209] op_sel_hi:[1,0]
	v_pk_mul_f32 v[112:113], v[112:113], v[208:209] op_sel_hi:[1,0]
	v_pk_mul_f32 v[106:107], v[106:107], v[208:209] op_sel_hi:[1,0]
	v_pk_mul_f32 v[108:109], v[108:109], v[208:209] op_sel_hi:[1,0]
	v_pk_mul_f32 v[102:103], v[102:103], v[208:209] op_sel_hi:[1,0]
	v_pk_mul_f32 v[104:105], v[104:105], v[208:209] op_sel_hi:[1,0]
	v_pk_mul_f32 v[98:99], v[98:99], v[208:209] op_sel_hi:[1,0]
	v_pk_mul_f32 v[100:101], v[100:101], v[208:209] op_sel_hi:[1,0]
	v_exp_f32_e32 v110, v110
	v_exp_f32_e32 v111, v111
	v_exp_f32_e32 v112, v112
	v_exp_f32_e32 v113, v113
	v_exp_f32_e32 v106, v106
	v_exp_f32_e32 v107, v107
	v_exp_f32_e32 v108, v108
	v_exp_f32_e32 v109, v109
	v_exp_f32_e32 v102, v102
	v_exp_f32_e32 v103, v103
	v_exp_f32_e32 v104, v104
	v_exp_f32_e32 v105, v105
	v_exp_f32_e32 v98, v98
	v_exp_f32_e32 v99, v99
	v_exp_f32_e32 v100, v100
	v_exp_f32_e32 v101, v101
	v_fmamk_f32 v209, v195, 0x3a800000, v187
	v_rsq_f32_e32 v209, v209
	v_pk_add_f32 v[110:111], v[110:111], 1.0 op_sel_hi:[1,0]
	v_pk_add_f32 v[112:113], v[112:113], 1.0 op_sel_hi:[1,0]
	v_pk_add_f32 v[106:107], v[106:107], 1.0 op_sel_hi:[1,0]
	v_pk_add_f32 v[108:109], v[108:109], 1.0 op_sel_hi:[1,0]
	v_min_f32_e32 v102, 0x5d5e0b6b, v102
	v_min_f32_e32 v103, 0x5d5e0b6b, v103
	v_min_f32_e32 v104, 0x5d5e0b6b, v104
	v_min_f32_e32 v105, 0x5d5e0b6b, v105
	v_min_f32_e32 v98, 0x5d5e0b6b, v98
	v_min_f32_e32 v99, 0x5d5e0b6b, v99
	v_min_f32_e32 v100, 0x5d5e0b6b, v100
	v_min_f32_e32 v101, 0x5d5e0b6b, v101
	v_rcp_f32_e32 v110, v110
	v_rcp_f32_e32 v111, v111
	v_rcp_f32_e32 v112, v112
	v_rcp_f32_e32 v113, v113
	v_rcp_f32_e32 v106, v106
	v_rcp_f32_e32 v107, v107
	v_rcp_f32_e32 v108, v108
	v_rcp_f32_e32 v109, v109
	v_pk_add_f32 v[102:103], v[102:103], 1.0 op_sel_hi:[1,0]
	v_pk_add_f32 v[104:105], v[104:105], 1.0 op_sel_hi:[1,0]
	v_pk_add_f32 v[98:99], v[98:99], 1.0 op_sel_hi:[1,0]
	v_pk_add_f32 v[100:101], v[100:101], 1.0 op_sel_hi:[1,0]
	v_mul_f32_e32 v208, 0xbfb8aa3b, v209
	v_pk_mul_f32 v[110:111], v[110:111], v[102:103]
	v_pk_mul_f32 v[112:113], v[112:113], v[104:105]
	v_pk_mul_f32 v[106:107], v[106:107], v[98:99]
; DI float fast_exp2(float x) { return __builtin_amdgcn_exp2f(x); }
; DI float fast_rcp(float x) { return __builtin_amdgcn_rcpf(x); }
;     DI void operator()(Acc& acc, const pg8::Unit& u, int wr, int wc, int fr, int fq, const Pre& pr) const {
;     ...
;                     const float nrl = -1.4426950408889634f * __builtin_amdgcn_rsqf(msq_of(pr.v[ai * 4 + m]));
;                     f32x4 rr[2], gc[2];
; #pragma unroll
;                     for (int n = 0; n < 2; ++n)
; #pragma unroll
;                         for (int i = 0; i < 4; ++i) {
;                             const float da = 1.0f + fast_exp2(acc[ai][0][m][n][i] * nrl), dc = 1.0f + fminf(fast_exp2(acc[ai][1][m][n][i] * nrl), 1e18f);
;                             rr[n][i] = dc * fast_rcp(da); gc[n][i] = fast_rcp(dc);
;                         }
;                     store8(MG + (size_t)row * 2048 + col, rr[0], rr[1]);
;                     store8(MG + (size_t)row * 2048 + 1024 + col, gc[0], gc[1]);
	v_pk_mul_f32 v[108:109], v[108:109], v[100:101]
	v_rcp_f32_e32 v102, v102
	v_rcp_f32_e32 v103, v103
	v_rcp_f32_e32 v104, v104
	v_rcp_f32_e32 v105, v105
	v_rcp_f32_e32 v98, v98
	v_rcp_f32_e32 v99, v99
	v_rcp_f32_e32 v100, v100
	v_rcp_f32_e32 v101, v101
	v_cvt_pk_bf16_f32 v110, v110, v111
	v_cvt_pk_bf16_f32 v111, v112, v113
	v_cvt_pk_bf16_f32 v112, v106, v107
	v_cvt_pk_bf16_f32 v113, v108, v109
	global_store_dwordx4 v199, v[110:113], s[48:49]
	v_cvt_pk_bf16_f32 v102, v102, v103
	v_cvt_pk_bf16_f32 v103, v104, v105
	v_cvt_pk_bf16_f32 v104, v98, v99
	v_cvt_pk_bf16_f32 v105, v100, v101
	global_store_dwordx4 v199, v[102:105], s[48:49] offset:2048
	v_pk_mul_f32 v[94:95], v[94:95], v[206:207] op_sel_hi:[1,0]
	v_pk_mul_f32 v[96:97], v[96:97], v[206:207] op_sel_hi:[1,0]
	v_pk_mul_f32 v[90:91], v[90:91], v[206:207] op_sel_hi:[1,0]
	v_pk_mul_f32 v[92:93], v[92:93], v[206:207] op_sel_hi:[1,0]
	v_pk_mul_f32 v[86:87], v[86:87], v[206:207] op_sel_hi:[1,0]
	v_pk_mul_f32 v[88:89], v[88:89], v[206:207] op_sel_hi:[1,0]
	v_pk_mul_f32 v[82:83], v[82:83], v[206:207] op_sel_hi:[1,0]
	v_pk_mul_f32 v[84:85], v[84:85], v[206:207] op_sel_hi:[1,0]
	v_exp_f32_e32 v94, v94
	v_exp_f32_e32 v95, v95
	v_exp_f32_e32 v96, v96
	v_exp_f32_e32 v97, v97
	v_exp_f32_e32 v90, v90
	v_exp_f32_e32 v91, v91
	v_exp_f32_e32 v92, v92
	v_exp_f32_e32 v93, v93
	v_exp_f32_e32 v86, v86
	v_exp_f32_e32 v87, v87
	v_exp_f32_e32 v88, v88
	v_exp_f32_e32 v89, v89
	v_exp_f32_e32 v82, v82
	v_exp_f32_e32 v83, v83
	v_exp_f32_e32 v84, v84
	v_exp_f32_e32 v85, v85
	v_fmamk_f32 v207, v194, 0x3a800000, v187
	v_rsq_f32_e32 v207, v207
	v_pk_add_f32 v[94:95], v[94:95], 1.0 op_sel_hi:[1,0]
	v_pk_add_f32 v[96:97], v[96:97], 1.0 op_sel_hi:[1,0]
	v_pk_add_f32 v[90:91], v[90:91], 1.0 op_sel_hi:[1,0]
	v_pk_add_f32 v[92:93], v[92:93], 1.0 op_sel_hi:[1,0]
	v_min_f32_e32 v86, 0x5d5e0b6b, v86
	v_min_f32_e32 v87, 0x5d5e0b6b, v87
	v_min_f32_e32 v88, 0x5d5e0b6b, v88
	v_min_f32_e32 v89, 0x5d5e0b6b, v89
	v_min_f32_e32 v82, 0x5d5e0b6b, v82
	v_min_f32_e32 v83, 0x5d5e0b6b, v83
	v_min_f32_e32 v84, 0x5d5e0b6b, v84
	v_min_f32_e32 v85, 0x5d5e0b6b, v85
	v_rcp_f32_e32 v94, v94
	v_rcp_f32_e32 v95, v95
	v_rcp_f32_e32 v96, v96
	v_rcp_f32_e32 v97, v97
	v_rcp_f32_e32 v90, v90
	v_rcp_f32_e32 v91, v91
	v_rcp_f32_e32 v92, v92
	v_rcp_f32_e32 v93, v93
	v_pk_add_f32 v[86:87], v[86:87], 1.0 op_sel_hi:[1,0]
	v_pk_add_f32 v[88:89], v[88:89], 1.0 op_sel_hi:[1,0]
	v_pk_add_f32 v[82:83], v[82:83], 1.0 op_sel_hi:[1,0]
	v_pk_add_f32 v[84:85], v[84:85], 1.0 op_sel_hi:[1,0]
	v_mul_f32_e32 v206, 0xbfb8aa3b, v207
	v_pk_mul_f32 v[94:95], v[94:95], v[86:87]
	v_pk_mul_f32 v[96:97], v[96:97], v[88:89]
	v_pk_mul_f32 v[90:91], v[90:91], v[82:83]
	v_pk_mul_f32 v[92:93], v[92:93], v[84:85]
	v_rcp_f32_e32 v86, v86
	v_rcp_f32_e32 v87, v87
	v_rcp_f32_e32 v88, v88
	v_rcp_f32_e32 v89, v89
	v_rcp_f32_e32 v82, v82
	v_rcp_f32_e32 v83, v83
	v_rcp_f32_e32 v84, v84
	v_rcp_f32_e32 v85, v85
	v_cvt_pk_bf16_f32 v94, v94, v95
	v_cvt_pk_bf16_f32 v95, v96, v97
	v_cvt_pk_bf16_f32 v96, v90, v91
	v_cvt_pk_bf16_f32 v97, v92, v93
	global_store_dwordx4 v200, v[94:97], s[48:49]
	v_cvt_pk_bf16_f32 v86, v86, v87
	v_cvt_pk_bf16_f32 v87, v88, v89
	v_cvt_pk_bf16_f32 v88, v82, v83
	v_cvt_pk_bf16_f32 v89, v84, v85
	global_store_dwordx4 v200, v[86:89], s[48:49] offset:2048
	v_pk_mul_f32 v[78:79], v[78:79], v[208:209] op_sel_hi:[1,0]
	v_pk_mul_f32 v[80:81], v[80:81], v[208:209] op_sel_hi:[1,0]
	v_pk_mul_f32 v[74:75], v[74:75], v[208:209] op_sel_hi:[1,0]
	v_pk_mul_f32 v[76:77], v[76:77], v[208:209] op_sel_hi:[1,0]
	v_pk_mul_f32 v[70:71], v[70:71], v[208:209] op_sel_hi:[1,0]
	v_pk_mul_f32 v[72:73], v[72:73], v[208:209] op_sel_hi:[1,0]
	v_pk_mul_f32 v[66:67], v[66:67], v[208:209] op_sel_hi:[1,0]
	v_pk_mul_f32 v[68:69], v[68:69], v[208:209] op_sel_hi:[1,0]
	v_exp_f32_e32 v78, v78
	v_exp_f32_e32 v79, v79
	v_exp_f32_e32 v80, v80
	v_exp_f32_e32 v81, v81
	v_exp_f32_e32 v74, v74
	v_exp_f32_e32 v75, v75
	v_exp_f32_e32 v76, v76
	v_exp_f32_e32 v77, v77
	v_exp_f32_e32 v70, v70
	v_exp_f32_e32 v71, v71
	v_exp_f32_e32 v72, v72
	v_exp_f32_e32 v73, v73
	v_exp_f32_e32 v66, v66
	v_exp_f32_e32 v67, v67
	v_exp_f32_e32 v68, v68
	v_exp_f32_e32 v69, v69
	v_fmamk_f32 v209, v193, 0x3a800000, v187
	v_rsq_f32_e32 v209, v209
	v_pk_add_f32 v[78:79], v[78:79], 1.0 op_sel_hi:[1,0]
	v_pk_add_f32 v[80:81], v[80:81], 1.0 op_sel_hi:[1,0]
	v_pk_add_f32 v[74:75], v[74:75], 1.0 op_sel_hi:[1,0]
	v_pk_add_f32 v[76:77], v[76:77], 1.0 op_sel_hi:[1,0]
	v_min_f32_e32 v70, 0x5d5e0b6b, v70
	v_min_f32_e32 v71, 0x5d5e0b6b, v71
	v_min_f32_e32 v72, 0x5d5e0b6b, v72
	v_min_f32_e32 v73, 0x5d5e0b6b, v73
	v_min_f32_e32 v66, 0x5d5e0b6b, v66
	v_min_f32_e32 v67, 0x5d5e0b6b, v67
	v_min_f32_e32 v68, 0x5d5e0b6b, v68
	v_min_f32_e32 v69, 0x5d5e0b6b, v69
	v_rcp_f32_e32 v78, v78
	v_rcp_f32_e32 v79, v79
	v_rcp_f32_e32 v80, v80
	v_rcp_f32_e32 v81, v81
	v_rcp_f32_e32 v74, v74
	v_rcp_f32_e32 v75, v75
	v_rcp_f32_e32 v76, v76
	v_rcp_f32_e32 v77, v77
	v_pk_add_f32 v[70:71], v[70:71], 1.0 op_sel_hi:[1,0]
	v_pk_add_f32 v[72:73], v[72:73], 1.0 op_sel_hi:[1,0]
	v_pk_add_f32 v[66:67], v[66:67], 1.0 op_sel_hi:[1,0]
	v_pk_add_f32 v[68:69], v[68:69], 1.0 op_sel_hi:[1,0]
	v_mul_f32_e32 v208, 0xbfb8aa3b, v209
	v_pk_mul_f32 v[78:79], v[78:79], v[70:71]
	v_pk_mul_f32 v[80:81], v[80:81], v[72:73]
	v_pk_mul_f32 v[74:75], v[74:75], v[66:67]
	v_pk_mul_f32 v[76:77], v[76:77], v[68:69]
	v_rcp_f32_e32 v70, v70
	v_rcp_f32_e32 v71, v71
	v_rcp_f32_e32 v72, v72
	v_rcp_f32_e32 v73, v73
	v_rcp_f32_e32 v66, v66
	v_rcp_f32_e32 v67, v67
	v_rcp_f32_e32 v68, v68
	v_rcp_f32_e32 v69, v69
	v_cvt_pk_bf16_f32 v78, v78, v79
	v_cvt_pk_bf16_f32 v79, v80, v81
	v_cvt_pk_bf16_f32 v80, v74, v75
; DI float fast_exp2(float x) { return __builtin_amdgcn_exp2f(x); }
; DI float fast_rcp(float x) { return __builtin_amdgcn_rcpf(x); }
;     DI void operator()(Acc& acc, const pg8::Unit& u, int wr, int wc, int fr, int fq, const Pre& pr) const {
;     ...
;                     const float nrl = -1.4426950408889634f * __builtin_amdgcn_rsqf(msq_of(pr.v[ai * 4 + m]));
;                     f32x4 rr[2], gc[2];
; #pragma unroll
;                     for (int n = 0; n < 2; ++n)
; #pragma unroll
;                         for (int i = 0; i < 4; ++i) {
;                             const float da = 1.0f + fast_exp2(acc[ai][0][m][n][i] * nrl), dc = 1.0f + fminf(fast_exp2(acc[ai][1][m][n][i] * nrl), 1e18f);
;                             rr[n][i] = dc * fast_rcp(da); gc[n][i] = fast_rcp(dc);
;                         }
;                     store8(MG + (size_t)row * 2048 + col, rr[0], rr[1]);
;                     store8(MG + (size_t)row * 2048 + 1024 + col, gc[0], gc[1]);
	v_cvt_pk_bf16_f32 v81, v76, v77
	global_store_dwordx4 v201, v[78:81], s[48:49]
	v_cvt_pk_bf16_f32 v70, v70, v71
	v_cvt_pk_bf16_f32 v71, v72, v73
	v_cvt_pk_bf16_f32 v72, v66, v67
	v_cvt_pk_bf16_f32 v73, v68, v69
	global_store_dwordx4 v201, v[70:73], s[48:49] offset:2048
	v_pk_mul_f32 v[62:63], v[62:63], v[206:207] op_sel_hi:[1,0]
	v_pk_mul_f32 v[64:65], v[64:65], v[206:207] op_sel_hi:[1,0]
	v_pk_mul_f32 v[58:59], v[58:59], v[206:207] op_sel_hi:[1,0]
	v_pk_mul_f32 v[60:61], v[60:61], v[206:207] op_sel_hi:[1,0]
	v_pk_mul_f32 v[54:55], v[54:55], v[206:207] op_sel_hi:[1,0]
	v_pk_mul_f32 v[56:57], v[56:57], v[206:207] op_sel_hi:[1,0]
	v_pk_mul_f32 v[50:51], v[50:51], v[206:207] op_sel_hi:[1,0]
	v_pk_mul_f32 v[52:53], v[52:53], v[206:207] op_sel_hi:[1,0]
	v_exp_f32_e32 v62, v62
	v_exp_f32_e32 v63, v63
	v_exp_f32_e32 v64, v64
	v_exp_f32_e32 v65, v65
	v_exp_f32_e32 v58, v58
	v_exp_f32_e32 v59, v59
	v_exp_f32_e32 v60, v60
	v_exp_f32_e32 v61, v61
	v_exp_f32_e32 v54, v54
	v_exp_f32_e32 v55, v55
	v_exp_f32_e32 v56, v56
	v_exp_f32_e32 v57, v57
	v_exp_f32_e32 v50, v50
	v_exp_f32_e32 v51, v51
	v_exp_f32_e32 v52, v52
	v_exp_f32_e32 v53, v53
	v_fmamk_f32 v207, v192, 0x3a800000, v187
	v_rsq_f32_e32 v207, v207
	v_pk_add_f32 v[62:63], v[62:63], 1.0 op_sel_hi:[1,0]
	v_pk_add_f32 v[64:65], v[64:65], 1.0 op_sel_hi:[1,0]
	v_pk_add_f32 v[58:59], v[58:59], 1.0 op_sel_hi:[1,0]
	v_pk_add_f32 v[60:61], v[60:61], 1.0 op_sel_hi:[1,0]
	v_min_f32_e32 v54, 0x5d5e0b6b, v54
	v_min_f32_e32 v55, 0x5d5e0b6b, v55
	v_min_f32_e32 v56, 0x5d5e0b6b, v56
	v_min_f32_e32 v57, 0x5d5e0b6b, v57
	v_min_f32_e32 v50, 0x5d5e0b6b, v50
	v_min_f32_e32 v51, 0x5d5e0b6b, v51
	v_min_f32_e32 v52, 0x5d5e0b6b, v52
	v_min_f32_e32 v53, 0x5d5e0b6b, v53
	v_rcp_f32_e32 v62, v62
	v_rcp_f32_e32 v63, v63
	v_rcp_f32_e32 v64, v64
	v_rcp_f32_e32 v65, v65
	v_rcp_f32_e32 v58, v58
	v_rcp_f32_e32 v59, v59
	v_rcp_f32_e32 v60, v60
	v_rcp_f32_e32 v61, v61
	v_pk_add_f32 v[54:55], v[54:55], 1.0 op_sel_hi:[1,0]
	v_pk_add_f32 v[56:57], v[56:57], 1.0 op_sel_hi:[1,0]
	v_pk_add_f32 v[50:51], v[50:51], 1.0 op_sel_hi:[1,0]
	v_pk_add_f32 v[52:53], v[52:53], 1.0 op_sel_hi:[1,0]
	v_mul_f32_e32 v206, 0xbfb8aa3b, v207
	v_pk_mul_f32 v[62:63], v[62:63], v[54:55]
	v_pk_mul_f32 v[64:65], v[64:65], v[56:57]
	v_pk_mul_f32 v[58:59], v[58:59], v[50:51]
	v_pk_mul_f32 v[60:61], v[60:61], v[52:53]
	v_rcp_f32_e32 v54, v54
	v_rcp_f32_e32 v55, v55
	v_rcp_f32_e32 v56, v56
	v_rcp_f32_e32 v57, v57
	v_rcp_f32_e32 v50, v50
	v_rcp_f32_e32 v51, v51
	v_rcp_f32_e32 v52, v52
	v_rcp_f32_e32 v53, v53
	v_cvt_pk_bf16_f32 v62, v62, v63
	v_cvt_pk_bf16_f32 v63, v64, v65
	v_cvt_pk_bf16_f32 v64, v58, v59
	v_cvt_pk_bf16_f32 v65, v60, v61
	global_store_dwordx4 v202, v[62:65], s[48:49]
	v_cvt_pk_bf16_f32 v54, v54, v55
	v_cvt_pk_bf16_f32 v55, v56, v57
	v_cvt_pk_bf16_f32 v56, v50, v51
	v_cvt_pk_bf16_f32 v57, v52, v53
	global_store_dwordx4 v202, v[54:57], s[48:49] offset:2048
	v_pk_mul_f32 v[46:47], v[46:47], v[208:209] op_sel_hi:[1,0]
	v_pk_mul_f32 v[48:49], v[48:49], v[208:209] op_sel_hi:[1,0]
	v_pk_mul_f32 v[42:43], v[42:43], v[208:209] op_sel_hi:[1,0]
	v_pk_mul_f32 v[44:45], v[44:45], v[208:209] op_sel_hi:[1,0]
	v_pk_mul_f32 v[38:39], v[38:39], v[208:209] op_sel_hi:[1,0]
	v_pk_mul_f32 v[40:41], v[40:41], v[208:209] op_sel_hi:[1,0]
	v_pk_mul_f32 v[34:35], v[34:35], v[208:209] op_sel_hi:[1,0]
	v_pk_mul_f32 v[36:37], v[36:37], v[208:209] op_sel_hi:[1,0]
	v_exp_f32_e32 v46, v46
	v_exp_f32_e32 v47, v47
	v_exp_f32_e32 v48, v48
	v_exp_f32_e32 v49, v49
	v_exp_f32_e32 v42, v42
	v_exp_f32_e32 v43, v43
	v_exp_f32_e32 v44, v44
	v_exp_f32_e32 v45, v45
	v_exp_f32_e32 v38, v38
	v_exp_f32_e32 v39, v39
	v_exp_f32_e32 v40, v40
	v_exp_f32_e32 v41, v41
	v_exp_f32_e32 v34, v34
	v_exp_f32_e32 v35, v35
	v_exp_f32_e32 v36, v36
	v_exp_f32_e32 v37, v37
	v_fmamk_f32 v209, v191, 0x3a800000, v187
	v_rsq_f32_e32 v209, v209
	v_pk_add_f32 v[46:47], v[46:47], 1.0 op_sel_hi:[1,0]
	v_pk_add_f32 v[48:49], v[48:49], 1.0 op_sel_hi:[1,0]
	v_pk_add_f32 v[42:43], v[42:43], 1.0 op_sel_hi:[1,0]
	v_pk_add_f32 v[44:45], v[44:45], 1.0 op_sel_hi:[1,0]
	v_min_f32_e32 v38, 0x5d5e0b6b, v38
	v_min_f32_e32 v39, 0x5d5e0b6b, v39
	v_min_f32_e32 v40, 0x5d5e0b6b, v40
	v_min_f32_e32 v41, 0x5d5e0b6b, v41
	v_min_f32_e32 v34, 0x5d5e0b6b, v34
	v_min_f32_e32 v35, 0x5d5e0b6b, v35
	v_min_f32_e32 v36, 0x5d5e0b6b, v36
	v_min_f32_e32 v37, 0x5d5e0b6b, v37
	v_rcp_f32_e32 v46, v46
	v_rcp_f32_e32 v47, v47
	v_rcp_f32_e32 v48, v48
	v_rcp_f32_e32 v49, v49
	v_rcp_f32_e32 v42, v42
	v_rcp_f32_e32 v43, v43
	v_rcp_f32_e32 v44, v44
	v_rcp_f32_e32 v45, v45
	v_pk_add_f32 v[38:39], v[38:39], 1.0 op_sel_hi:[1,0]
	v_pk_add_f32 v[40:41], v[40:41], 1.0 op_sel_hi:[1,0]
	v_pk_add_f32 v[34:35], v[34:35], 1.0 op_sel_hi:[1,0]
	v_pk_add_f32 v[36:37], v[36:37], 1.0 op_sel_hi:[1,0]
	v_mul_f32_e32 v208, 0xbfb8aa3b, v209
	v_pk_mul_f32 v[46:47], v[46:47], v[38:39]
	v_pk_mul_f32 v[48:49], v[48:49], v[40:41]
	v_pk_mul_f32 v[42:43], v[42:43], v[34:35]
	v_pk_mul_f32 v[44:45], v[44:45], v[36:37]
	v_rcp_f32_e32 v38, v38
	v_rcp_f32_e32 v39, v39
	v_rcp_f32_e32 v40, v40
	v_rcp_f32_e32 v41, v41
	v_rcp_f32_e32 v34, v34
	v_rcp_f32_e32 v35, v35
	v_rcp_f32_e32 v36, v36
	v_rcp_f32_e32 v37, v37
	v_cvt_pk_bf16_f32 v46, v46, v47
	v_cvt_pk_bf16_f32 v47, v48, v49
; DI float fast_exp2(float x) { return __builtin_amdgcn_exp2f(x); }
; DI float fast_rcp(float x) { return __builtin_amdgcn_rcpf(x); }
;     DI void operator()(Acc& acc, const pg8::Unit& u, int wr, int wc, int fr, int fq, const Pre& pr) const {
;     ...
;                     const float nrl = -1.4426950408889634f * __builtin_amdgcn_rsqf(msq_of(pr.v[ai * 4 + m]));
;                     f32x4 rr[2], gc[2];
; #pragma unroll
;                     for (int n = 0; n < 2; ++n)
; #pragma unroll
;                         for (int i = 0; i < 4; ++i) {
;                             const float da = 1.0f + fast_exp2(acc[ai][0][m][n][i] * nrl), dc = 1.0f + fminf(fast_exp2(acc[ai][1][m][n][i] * nrl), 1e18f);
;                             rr[n][i] = dc * fast_rcp(da); gc[n][i] = fast_rcp(dc);
;                         }
;                     store8(MG + (size_t)row * 2048 + col, rr[0], rr[1]);
;                     store8(MG + (size_t)row * 2048 + 1024 + col, gc[0], gc[1]);
	v_cvt_pk_bf16_f32 v48, v42, v43
	v_cvt_pk_bf16_f32 v49, v44, v45
	global_store_dwordx4 v203, v[46:49], s[48:49]
	v_cvt_pk_bf16_f32 v38, v38, v39
	v_cvt_pk_bf16_f32 v39, v40, v41
	v_cvt_pk_bf16_f32 v40, v34, v35
	v_cvt_pk_bf16_f32 v41, v36, v37
	global_store_dwordx4 v203, v[38:41], s[48:49] offset:2048
	v_pk_mul_f32 v[30:31], v[30:31], v[206:207] op_sel_hi:[1,0]
	v_pk_mul_f32 v[32:33], v[32:33], v[206:207] op_sel_hi:[1,0]
	v_pk_mul_f32 v[26:27], v[26:27], v[206:207] op_sel_hi:[1,0]
	v_pk_mul_f32 v[28:29], v[28:29], v[206:207] op_sel_hi:[1,0]
	v_pk_mul_f32 v[22:23], v[22:23], v[206:207] op_sel_hi:[1,0]
	v_pk_mul_f32 v[24:25], v[24:25], v[206:207] op_sel_hi:[1,0]
	v_pk_mul_f32 v[18:19], v[18:19], v[206:207] op_sel_hi:[1,0]
	v_pk_mul_f32 v[20:21], v[20:21], v[206:207] op_sel_hi:[1,0]
	v_exp_f32_e32 v30, v30
	v_exp_f32_e32 v31, v31
	v_exp_f32_e32 v32, v32
	v_exp_f32_e32 v33, v33
	v_exp_f32_e32 v26, v26
	v_exp_f32_e32 v27, v27
	v_exp_f32_e32 v28, v28
	v_exp_f32_e32 v29, v29
	v_exp_f32_e32 v22, v22
	v_exp_f32_e32 v23, v23
	v_exp_f32_e32 v24, v24
	v_exp_f32_e32 v25, v25
	v_exp_f32_e32 v18, v18
	v_exp_f32_e32 v19, v19
	v_exp_f32_e32 v20, v20
	v_exp_f32_e32 v21, v21
	v_pk_add_f32 v[30:31], v[30:31], 1.0 op_sel_hi:[1,0]
	v_pk_add_f32 v[32:33], v[32:33], 1.0 op_sel_hi:[1,0]
	v_pk_add_f32 v[26:27], v[26:27], 1.0 op_sel_hi:[1,0]
	v_pk_add_f32 v[28:29], v[28:29], 1.0 op_sel_hi:[1,0]
	v_min_f32_e32 v22, 0x5d5e0b6b, v22
	v_min_f32_e32 v23, 0x5d5e0b6b, v23
	v_min_f32_e32 v24, 0x5d5e0b6b, v24
	v_min_f32_e32 v25, 0x5d5e0b6b, v25
	v_min_f32_e32 v18, 0x5d5e0b6b, v18
	v_min_f32_e32 v19, 0x5d5e0b6b, v19
	v_min_f32_e32 v20, 0x5d5e0b6b, v20
	v_min_f32_e32 v21, 0x5d5e0b6b, v21
	v_rcp_f32_e32 v30, v30
	v_rcp_f32_e32 v31, v31
	v_rcp_f32_e32 v32, v32
	v_rcp_f32_e32 v33, v33
	v_rcp_f32_e32 v26, v26
	v_rcp_f32_e32 v27, v27
	v_rcp_f32_e32 v28, v28
	v_rcp_f32_e32 v29, v29
	v_pk_add_f32 v[22:23], v[22:23], 1.0 op_sel_hi:[1,0]
	v_pk_add_f32 v[24:25], v[24:25], 1.0 op_sel_hi:[1,0]
	v_pk_add_f32 v[18:19], v[18:19], 1.0 op_sel_hi:[1,0]
	v_pk_add_f32 v[20:21], v[20:21], 1.0 op_sel_hi:[1,0]
	v_pk_mul_f32 v[30:31], v[30:31], v[22:23]
	v_pk_mul_f32 v[32:33], v[32:33], v[24:25]
	v_pk_mul_f32 v[26:27], v[26:27], v[18:19]
	v_pk_mul_f32 v[28:29], v[28:29], v[20:21]
	v_rcp_f32_e32 v22, v22
	v_rcp_f32_e32 v23, v23
	v_rcp_f32_e32 v24, v24
	v_rcp_f32_e32 v25, v25
	v_rcp_f32_e32 v18, v18
	v_rcp_f32_e32 v19, v19
	v_rcp_f32_e32 v20, v20
	v_rcp_f32_e32 v21, v21
	v_cvt_pk_bf16_f32 v30, v30, v31
	v_cvt_pk_bf16_f32 v31, v32, v33
	v_cvt_pk_bf16_f32 v32, v26, v27
	v_cvt_pk_bf16_f32 v33, v28, v29
	global_store_dwordx4 v204, v[30:33], s[48:49]
	v_cvt_pk_bf16_f32 v22, v22, v23
	v_cvt_pk_bf16_f32 v23, v24, v25
	v_cvt_pk_bf16_f32 v24, v18, v19
	v_cvt_pk_bf16_f32 v25, v20, v21
	global_store_dwordx4 v204, v[22:25], s[48:49] offset:2048
	v_pk_mul_f32 v[14:15], v[14:15], v[208:209] op_sel_hi:[1,0]
	v_pk_mul_f32 v[16:17], v[16:17], v[208:209] op_sel_hi:[1,0]
	v_pk_mul_f32 v[10:11], v[10:11], v[208:209] op_sel_hi:[1,0]
	v_pk_mul_f32 v[12:13], v[12:13], v[208:209] op_sel_hi:[1,0]
	v_pk_mul_f32 v[6:7], v[6:7], v[208:209] op_sel_hi:[1,0]
	v_pk_mul_f32 v[8:9], v[8:9], v[208:209] op_sel_hi:[1,0]
	v_pk_mul_f32 v[2:3], v[2:3], v[208:209] op_sel_hi:[1,0]
	v_pk_mul_f32 v[4:5], v[4:5], v[208:209] op_sel_hi:[1,0]
	v_exp_f32_e32 v14, v14
	v_exp_f32_e32 v15, v15
	v_exp_f32_e32 v16, v16
	v_exp_f32_e32 v17, v17
	v_exp_f32_e32 v10, v10
	v_exp_f32_e32 v11, v11
	v_exp_f32_e32 v12, v12
	v_exp_f32_e32 v13, v13
	v_exp_f32_e32 v6, v6
	v_exp_f32_e32 v7, v7
	v_exp_f32_e32 v8, v8
	v_exp_f32_e32 v9, v9
	v_exp_f32_e32 v2, v2
	v_exp_f32_e32 v3, v3
	v_exp_f32_e32 v4, v4
	v_exp_f32_e32 v5, v5
	v_pk_add_f32 v[14:15], v[14:15], 1.0 op_sel_hi:[1,0]
	v_pk_add_f32 v[16:17], v[16:17], 1.0 op_sel_hi:[1,0]
	v_pk_add_f32 v[10:11], v[10:11], 1.0 op_sel_hi:[1,0]
	v_pk_add_f32 v[12:13], v[12:13], 1.0 op_sel_hi:[1,0]
	v_min_f32_e32 v6, 0x5d5e0b6b, v6
	v_min_f32_e32 v7, 0x5d5e0b6b, v7
	v_min_f32_e32 v8, 0x5d5e0b6b, v8
	v_min_f32_e32 v9, 0x5d5e0b6b, v9
	v_min_f32_e32 v2, 0x5d5e0b6b, v2
	v_min_f32_e32 v3, 0x5d5e0b6b, v3
	v_min_f32_e32 v4, 0x5d5e0b6b, v4
	v_min_f32_e32 v5, 0x5d5e0b6b, v5
	v_rcp_f32_e32 v14, v14
	v_rcp_f32_e32 v15, v15
	v_rcp_f32_e32 v16, v16
	v_rcp_f32_e32 v17, v17
	v_rcp_f32_e32 v10, v10
	v_rcp_f32_e32 v11, v11
	v_rcp_f32_e32 v12, v12
	v_rcp_f32_e32 v13, v13
	v_pk_add_f32 v[6:7], v[6:7], 1.0 op_sel_hi:[1,0]
	v_pk_add_f32 v[8:9], v[8:9], 1.0 op_sel_hi:[1,0]
	v_pk_add_f32 v[2:3], v[2:3], 1.0 op_sel_hi:[1,0]
	v_pk_add_f32 v[4:5], v[4:5], 1.0 op_sel_hi:[1,0]
	v_pk_mul_f32 v[14:15], v[14:15], v[6:7]
	v_pk_mul_f32 v[16:17], v[16:17], v[8:9]
	v_pk_mul_f32 v[10:11], v[10:11], v[2:3]
	v_pk_mul_f32 v[12:13], v[12:13], v[4:5]
	v_rcp_f32_e32 v6, v6
	v_rcp_f32_e32 v7, v7
	v_rcp_f32_e32 v8, v8
	v_rcp_f32_e32 v9, v9
	v_rcp_f32_e32 v2, v2
	v_rcp_f32_e32 v3, v3
	v_rcp_f32_e32 v4, v4
	v_rcp_f32_e32 v5, v5
	v_cvt_pk_bf16_f32 v14, v14, v15
	v_cvt_pk_bf16_f32 v15, v16, v17
	v_cvt_pk_bf16_f32 v16, v10, v11
	v_cvt_pk_bf16_f32 v17, v12, v13
	global_store_dwordx4 v205, v[14:17], s[48:49]
	v_cvt_pk_bf16_f32 v6, v6, v7
	v_cvt_pk_bf16_f32 v7, v8, v9
	v_cvt_pk_bf16_f32 v8, v2, v3
	v_cvt_pk_bf16_f32 v9, v4, v5
	global_store_dwordx4 v205, v[6:9], s[48:49] offset:2048

;     DI void operator()(Acc& acc, const pg8::Unit& u, int wr, int wc, int fr, int fq, const Pre& pr) const {
;     ...
;                     const int row = u.pm * 256 + ai * 128 + wr * 64 + m * 16 + fr;
;                     const float rs = __builtin_amdgcn_rsqf(msq_of(pr.v[ai * 4 + m]));
;                     f32x4 v[2][2];
; #pragma unroll
;                     for (int bj = 0; bj < 2; ++bj)
; #pragma unroll
;                         for (int n = 0; n < 2; ++n) v[bj][n] = acc[ai][bj][m][n] * rs;
;                     if (do_norm) {
;                         float ss = 0.f;
; #pragma unroll
;                         for (int bj = 0; bj < 2; ++bj)
; #pragma unroll
;                             for (int n = 0; n < 2; ++n) ss += (v[bj][n][0] * v[bj][n][0] + v[bj][n][1] * v[bj][n][1]) + (v[bj][n][2] * v[bj][n][2] + v[bj][n][3] * v[bj][n][3]);
;                         ss += __shfl_xor(ss, 16); ss += __shfl_xor(ss, 32);
;                         const float hr = __builtin_amdgcn_rsqf(ss * (1.0f / 64.0f) + NORM_EPS);
; #pragma unroll
;                         for (int bj = 0; bj < 2; ++bj)
; #pragma unroll
;                             for (int n = 0; n < 2; ++n) v[bj][n] = v[bj][n] * hr * gn[bj][n];
;                         const int s = row & (SEQ - 1);
; #pragma unroll
;                         for (int n = 0; n < 2; ++n) {
;                             f32x4 pr;
; #pragma unroll
;                             for (int i = 0; i < 4; ++i) pr[i] = __shfl_xor(v[0][n][i], 16);
;                             if (fq < 2) {
;                                 const f32x4 cs = *(const f32x4*)(rope + s * 16 + 4 * n), sn = *(const f32x4*)(rope + s * 16 + 8 + 4 * n);
;                                 v[0][n] = (fq == 0) ? (v[0][n] * cs - pr * sn) : (v[0][n] * cs + pr * sn);
;                             }
;                         }
.LBB0_413:
	s_waitcnt vmcnt(0)
	v_fmamk_f32 v156, v174, 0x3a800000, v187
	v_rsq_f32_e32 v156, v156
	s_and_b64 vcc, exec, s[10:11]
	v_pk_mul_f32 v[128:129], v[156:157], v[128:129] op_sel_hi:[0,1]
	v_pk_mul_f32 v[126:127], v[156:157], v[126:127] op_sel_hi:[0,1]
	v_pk_mul_f32 v[124:125], v[156:157], v[124:125] op_sel_hi:[0,1]
	v_pk_mul_f32 v[122:123], v[156:157], v[122:123] op_sel_hi:[0,1]
	v_pk_mul_f32 v[120:121], v[156:157], v[120:121] op_sel_hi:[0,1]
	v_pk_mul_f32 v[118:119], v[156:157], v[118:119] op_sel_hi:[0,1]
	v_pk_mul_f32 v[116:117], v[156:157], v[116:117] op_sel_hi:[0,1]
	v_pk_mul_f32 v[114:115], v[156:157], v[114:115] op_sel_hi:[0,1]
	s_cbranch_vccnz .LBB0_419
	v_lshlrev_b32_e32 v222, 6, v170
	v_and_b32_e32 v222, 0x1ffc0, v222
	global_load_dwordx4 v[206:209], v222, s[40:41] offset:32
	global_load_dwordx4 v[210:213], v222, s[40:41]
	global_load_dwordx4 v[214:217], v222, s[40:41] offset:48
	global_load_dwordx4 v[218:221], v222, s[40:41] offset:16
	v_pk_mul_f32 v[172:173], v[128:129], v[128:129]
	v_pk_mul_f32 v[174:175], v[126:127], v[126:127]
	v_mul_f32_e32 v156, v114, v114
	v_pk_mov_b32 v[176:177], v[174:175], v[172:173] op_sel:[1,0]
	v_mov_b32_e32 v175, v173
	v_pk_add_f32 v[172:173], v[176:177], v[174:175]
	v_pk_mul_f32 v[174:175], v[124:125], v[124:125]
	v_pk_mul_f32 v[176:177], v[122:123], v[122:123]
	v_pk_add_f32 v[172:173], v[172:173], v[172:173] op_sel:[0,1] op_sel_hi:[1,0]
	v_pk_mov_b32 v[178:179], v[176:177], v[174:175] op_sel:[1,0]
	v_mov_b32_e32 v177, v175
	v_pk_add_f32 v[174:175], v[178:179], v[176:177]
	v_mul_f32_e32 v176, v115, v115
	v_pk_add_f32 v[174:175], v[174:175], v[174:175] op_sel:[0,1] op_sel_hi:[1,0]
	v_mov_b32_e32 v173, v156
	v_mov_b32_e32 v175, v176
	v_mul_f32_e32 v156, v119, v119
	v_mul_f32_e32 v177, v116, v116
	v_pk_add_f32 v[172:173], v[172:173], v[174:175]
	v_pk_fma_f32 v[174:175], v[118:119], v[118:119], v[156:157] op_sel_hi:[1,1,0]
	v_mul_f32_e32 v156, v121, v121
	v_mul_f32_e32 v178, v117, v117
	v_mov_b32_e32 v175, v177
	v_pk_fma_f32 v[176:177], v[120:121], v[120:121], v[156:157] op_sel_hi:[1,1,0]
	s_nop 0
	v_mov_b32_e32 v177, v178
	v_pk_add_f32 v[174:175], v[174:175], v[176:177]
	s_nop 0
	v_pk_add_f32 v[172:173], v[172:173], v[174:175]
	s_nop 0
	v_add_f32_e32 v156, v172, v173
	v_and_b32_e32 v173, 64, v190
	v_xor_b32_e32 v172, 16, v190
	v_add_u32_e32 v173, 64, v173
	v_cmp_lt_i32_e32 vcc, v172, v173
	s_nop 1
	v_cndmask_b32_e32 v172, v190, v172, vcc
	v_lshlrev_b32_e32 v181, 2, v172
	v_mov_b32_e32 v172, v156
	s_nop 1
	v_permlane16_swap_b32_e32 v172, v156
	v_add_f32_e32 v156, v156, v172
	v_xor_b32_e32 v172, 32, v190
	v_cmp_lt_i32_e32 vcc, v172, v173
	s_nop 1
	v_cndmask_b32_e32 v172, v190, v172, vcc
	v_lshlrev_b32_e32 v172, 2, v172
	v_mov_b32_e32 v172, v156
	s_nop 1
	v_permlane32_swap_b32_e32 v172, v156
	v_add_f32_e32 v156, v156, v172
	v_fmamk_f32 v156, v156, 0x3c800000, v187
	v_rsq_f32_e32 v172, v156
	v_lshlrev_b32_e32 v156, 6, v170
	v_and_b32_e32 v156, 0x1f3c0, v156
	v_lshl_add_u64 v[176:177], s[40:41], 0, v[156:157]
	v_pk_mul_f32 v[126:127], v[126:127], v[172:173] op_sel_hi:[1,0]
	v_pk_mul_f32 v[128:129], v[128:129], v[172:173] op_sel_hi:[1,0]
	v_pk_mul_f32 v[126:127], v[142:143], v[126:127]
	v_pk_mul_f32 v[128:129], v[144:145], v[128:129]
	ds_bpermute_b32 v174, v181, v126
	ds_bpermute_b32 v175, v181, v127
	ds_bpermute_b32 v178, v181, v128
	ds_bpermute_b32 v179, v181, v129
	s_and_saveexec_b64 s[68:69], s[4:5]
	s_cbranch_execz .LBB0_416
	s_waitcnt vmcnt(2)
	v_mov_b64_e32 v[198:199], v[206:207]
	v_mov_b64_e32 v[200:201], v[208:209]
	v_mov_b64_e32 v[202:203], v[210:211]
	v_mov_b64_e32 v[204:205], v[212:213]
	s_waitcnt lgkmcnt(0)
	v_pk_mul_f32 v[178:179], v[200:201], v[178:179]
	v_pk_mul_f32 v[174:175], v[198:199], v[174:175]
	v_xor_b32_e32 v156, 0x80000000, v178
	v_xor_b32_e32 v173, 0x80000000, v179
	v_xor_b32_e32 v180, 0x80000000, v174
	v_xor_b32_e32 v198, 0x80000000, v175
	v_cndmask_b32_e64 v179, v179, v173, s[6:7]
	v_cndmask_b32_e64 v178, v178, v156, s[6:7]
	v_cndmask_b32_e64 v175, v175, v198, s[6:7]
	v_cndmask_b32_e64 v174, v174, v180, s[6:7]
	v_pk_fma_f32 v[128:129], v[128:129], v[204:205], v[178:179]
	v_pk_fma_f32 v[126:127], v[126:127], v[202:203], v[174:175]

;     DI void operator()(Acc& acc, const pg8::Unit& u, int wr, int wc, int fr, int fq, const Pre& pr) const {
;     ...
;                     const int row = u.pm * 256 + ai * 128 + wr * 64 + m * 16 + fr;
;                     const float rs = __builtin_amdgcn_rsqf(msq_of(pr.v[ai * 4 + m]));
;                     f32x4 v[2][2];
; #pragma unroll
;                     for (int bj = 0; bj < 2; ++bj)
; #pragma unroll
;                         for (int n = 0; n < 2; ++n) v[bj][n] = acc[ai][bj][m][n] * rs;
;                     if (do_norm) {
;                         float ss = 0.f;
; #pragma unroll
;                         for (int bj = 0; bj < 2; ++bj)
; #pragma unroll
;                             for (int n = 0; n < 2; ++n) ss += (v[bj][n][0] * v[bj][n][0] + v[bj][n][1] * v[bj][n][1]) + (v[bj][n][2] * v[bj][n][2] + v[bj][n][3] * v[bj][n][3]);
;                         ss += __shfl_xor(ss, 16); ss += __shfl_xor(ss, 32);
;                         const float hr = __builtin_amdgcn_rsqf(ss * (1.0f / 64.0f) + NORM_EPS);
; #pragma unroll
;                         for (int bj = 0; bj < 2; ++bj)
; #pragma unroll
;                             for (int n = 0; n < 2; ++n) v[bj][n] = v[bj][n] * hr * gn[bj][n];
;                         const int s = row & (SEQ - 1);
; #pragma unroll
;                         for (int n = 0; n < 2; ++n) {
;                             f32x4 pr;
; #pragma unroll
;                             for (int i = 0; i < 4; ++i) pr[i] = __shfl_xor(v[0][n][i], 16);
;                             if (fq < 2) {
;                                 const f32x4 cs = *(const f32x4*)(rope + s * 16 + 4 * n), sn = *(const f32x4*)(rope + s * 16 + 8 + 4 * n);
;                                 v[0][n] = (fq == 0) ? (v[0][n] * cs - pr * sn) : (v[0][n] * cs + pr * sn);
;                             }
;                         }
;                     }
;                     bf16_t* dst;
;                     if (pn < 2) dst = Q + (size_t)row * 512 + (4 * pn + wc) * 64 + 8 * fq;
;                     else { const int b = row >> 11, sq = row & (SEQ - 1); dst = KV + (size_t)slot * KV_SLOT + ((size_t)((b * 2 + gidx) * SEQ + sq)) * 64 + 8 * fq; }
; #pragma unroll
;                     for (int bj = 0; bj < 2; ++bj) store8(dst + 32 * bj, v[bj][0] * scale, v[bj][1] * scale);
.LBB0_423:
	v_lshlrev_b32_e32 v156, 1, v158
	v_pk_mul_f32 v[128:129], s[64:65], v[128:129] op_sel_hi:[0,1]
	v_pk_mul_f32 v[126:127], s[64:65], v[126:127] op_sel_hi:[0,1]
	v_pk_mul_f32 v[174:175], s[64:65], v[124:125] op_sel_hi:[0,1]
	v_pk_mul_f32 v[124:125], s[64:65], v[122:123] op_sel_hi:[0,1]
	v_lshl_add_u64 v[172:173], v[172:173], 0, v[156:157]
	v_cvt_pk_bf16_f32 v122, v126, v127
	v_cvt_pk_bf16_f32 v123, v128, v129
	v_cvt_pk_bf16_f32 v124, v124, v125
	v_cvt_pk_bf16_f32 v125, v174, v175
	v_pk_mul_f32 v[118:119], s[64:65], v[118:119] op_sel_hi:[0,1]
	global_store_dwordx4 v[172:173], v[122:125], off
	v_pk_mul_f32 v[120:121], s[64:65], v[120:121] op_sel_hi:[0,1]
	s_and_b64 vcc, exec, s[10:11]
	v_pk_mul_f32 v[122:123], s[64:65], v[116:117] op_sel_hi:[0,1]
	v_pk_mul_f32 v[116:117], s[64:65], v[114:115] op_sel_hi:[0,1]
	v_cvt_pk_bf16_f32 v114, v118, v119
	v_fmamk_f32 v118, v197, 0x3a800000, v187
	v_rsq_f32_e32 v118, v118
	v_cvt_pk_bf16_f32 v115, v120, v121
	v_cvt_pk_bf16_f32 v116, v116, v117
	v_cvt_pk_bf16_f32 v117, v122, v123
	global_store_dwordx4 v[172:173], v[114:117], off offset:64
	v_pk_mul_f32 v[112:113], v[118:119], v[112:113] op_sel_hi:[0,1]
	v_pk_mul_f32 v[110:111], v[118:119], v[110:111] op_sel_hi:[0,1]
	v_pk_mul_f32 v[108:109], v[118:119], v[108:109] op_sel_hi:[0,1]
	v_pk_mul_f32 v[106:107], v[118:119], v[106:107] op_sel_hi:[0,1]
	v_pk_mul_f32 v[104:105], v[118:119], v[104:105] op_sel_hi:[0,1]
	v_pk_mul_f32 v[102:103], v[118:119], v[102:103] op_sel_hi:[0,1]
	v_pk_mul_f32 v[100:101], v[118:119], v[100:101] op_sel_hi:[0,1]
	v_pk_mul_f32 v[98:99], v[118:119], v[98:99] op_sel_hi:[0,1]
	v_or_b32_e32 v114, 16, v170
	s_cbranch_vccnz .LBB0_429
	v_lshlrev_b32_e32 v222, 6, v114
	v_and_b32_e32 v222, 0x1ffc0, v222
	global_load_dwordx4 v[206:209], v222, s[40:41] offset:32
	global_load_dwordx4 v[210:213], v222, s[40:41]
	global_load_dwordx4 v[214:217], v222, s[40:41] offset:48
	global_load_dwordx4 v[218:221], v222, s[40:41] offset:16
	v_pk_mul_f32 v[116:117], v[112:113], v[112:113]
	v_pk_mul_f32 v[118:119], v[110:111], v[110:111]
	v_mul_f32_e32 v115, v98, v98
	v_pk_mov_b32 v[120:121], v[118:119], v[116:117] op_sel:[1,0]
	v_mov_b32_e32 v119, v117
	v_pk_add_f32 v[116:117], v[120:121], v[118:119]
	v_pk_mul_f32 v[118:119], v[108:109], v[108:109]
	v_pk_mul_f32 v[120:121], v[106:107], v[106:107]
	v_pk_add_f32 v[116:117], v[116:117], v[116:117] op_sel:[0,1] op_sel_hi:[1,0]
	v_pk_mov_b32 v[122:123], v[120:121], v[118:119] op_sel:[1,0]
	v_mov_b32_e32 v121, v119
	v_pk_add_f32 v[118:119], v[122:123], v[120:121]
	v_mul_f32_e32 v120, v99, v99
	v_pk_add_f32 v[118:119], v[118:119], v[118:119] op_sel:[0,1] op_sel_hi:[1,0]
	v_mov_b32_e32 v117, v115
	v_mov_b32_e32 v119, v120
	v_pk_add_f32 v[116:117], v[116:117], v[118:119]
	v_mul_f32_e32 v118, v103, v103
	v_mul_f32_e32 v121, v100, v100
	v_pk_fma_f32 v[118:119], v[102:103], v[102:103], v[118:119] op_sel_hi:[1,1,0]
	v_mul_f32_e32 v120, v105, v105
	v_mul_f32_e32 v122, v101, v101
	v_mov_b32_e32 v119, v121
	v_pk_fma_f32 v[120:121], v[104:105], v[104:105], v[120:121] op_sel_hi:[1,1,0]
	v_xor_b32_e32 v115, 16, v190
	v_mov_b32_e32 v121, v122
	v_pk_add_f32 v[118:119], v[118:119], v[120:121]
	v_mov_b32_e32 v121, v157
	v_pk_add_f32 v[116:117], v[116:117], v[118:119]
	s_nop 0
	v_add_f32_e32 v116, v116, v117
	v_and_b32_e32 v117, 64, v190
	v_add_u32_e32 v117, 64, v117
	v_cmp_lt_i32_e32 vcc, v115, v117
	s_nop 1
	v_cndmask_b32_e32 v115, v190, v115, vcc
	v_lshlrev_b32_e32 v115, 2, v115
	v_mov_b32_e32 v118, v116
	s_nop 1
	v_permlane16_swap_b32_e32 v118, v116
	v_add_f32_e32 v116, v116, v118
	v_xor_b32_e32 v118, 32, v190
	v_cmp_lt_i32_e32 vcc, v118, v117
	s_nop 1
	v_cndmask_b32_e32 v117, v190, v118, vcc
	v_lshlrev_b32_e32 v117, 2, v117
	v_mov_b32_e32 v117, v116
	s_nop 1
	v_permlane32_swap_b32_e32 v117, v116
	v_add_f32_e32 v116, v116, v117
	v_fmamk_f32 v116, v116, 0x3c800000, v187
	v_rsq_f32_e32 v116, v116
	s_nop 0
	v_pk_mul_f32 v[110:111], v[110:111], v[116:117] op_sel_hi:[1,0]
	v_pk_mul_f32 v[112:113], v[112:113], v[116:117] op_sel_hi:[1,0]
	v_pk_mul_f32 v[110:111], v[142:143], v[110:111]
	v_pk_mul_f32 v[112:113], v[144:145], v[112:113]
	ds_bpermute_b32 v118, v115, v110
	ds_bpermute_b32 v119, v115, v111
	ds_bpermute_b32 v122, v115, v112
	ds_bpermute_b32 v123, v115, v113
	v_lshlrev_b32_e32 v117, 6, v114
	v_and_b32_e32 v120, 0x1f7c0, v117
	v_lshl_add_u64 v[120:121], s[40:41], 0, v[120:121]
	s_and_saveexec_b64 s[12:13], s[4:5]
	s_cbranch_execz .LBB0_426
	s_waitcnt vmcnt(2)
	v_mov_b64_e32 v[124:125], v[206:207]
	v_mov_b64_e32 v[126:127], v[208:209]
	v_mov_b64_e32 v[172:173], v[210:211]
	v_mov_b64_e32 v[174:175], v[212:213]
	s_waitcnt lgkmcnt(0)
	v_pk_mul_f32 v[122:123], v[126:127], v[122:123]
	v_pk_mul_f32 v[118:119], v[124:125], v[118:119]
	v_xor_b32_e32 v117, 0x80000000, v122
	v_xor_b32_e32 v124, 0x80000000, v123
	v_xor_b32_e32 v125, 0x80000000, v118
	v_xor_b32_e32 v126, 0x80000000, v119
	v_cndmask_b32_e64 v123, v123, v124, s[6:7]
	v_cndmask_b32_e64 v122, v122, v117, s[6:7]
	v_cndmask_b32_e64 v119, v119, v126, s[6:7]
	v_cndmask_b32_e64 v118, v118, v125, s[6:7]
	v_pk_fma_f32 v[112:113], v[112:113], v[174:175], v[122:123]
	v_pk_fma_f32 v[110:111], v[110:111], v[172:173], v[118:119]

;     DI void operator()(Acc& acc, const pg8::Unit& u, int wr, int wc, int fr, int fq, const Pre& pr) const {
;     ...
;                     const int row = u.pm * 256 + ai * 128 + wr * 64 + m * 16 + fr;
;                     const float rs = __builtin_amdgcn_rsqf(msq_of(pr.v[ai * 4 + m]));
;                     f32x4 v[2][2];
; #pragma unroll
;                     for (int bj = 0; bj < 2; ++bj)
; #pragma unroll
;                         for (int n = 0; n < 2; ++n) v[bj][n] = acc[ai][bj][m][n] * rs;
;                     if (do_norm) {
;                         float ss = 0.f;
; #pragma unroll
;                         for (int bj = 0; bj < 2; ++bj)
; #pragma unroll
;                             for (int n = 0; n < 2; ++n) ss += (v[bj][n][0] * v[bj][n][0] + v[bj][n][1] * v[bj][n][1]) + (v[bj][n][2] * v[bj][n][2] + v[bj][n][3] * v[bj][n][3]);
;                         ss += __shfl_xor(ss, 16); ss += __shfl_xor(ss, 32);
;                         const float hr = __builtin_amdgcn_rsqf(ss * (1.0f / 64.0f) + NORM_EPS);
; #pragma unroll
;                         for (int bj = 0; bj < 2; ++bj)
; #pragma unroll
;                             for (int n = 0; n < 2; ++n) v[bj][n] = v[bj][n] * hr * gn[bj][n];
;                         const int s = row & (SEQ - 1);
; #pragma unroll
;                         for (int n = 0; n < 2; ++n) {
;                             f32x4 pr;
; #pragma unroll
;                             for (int i = 0; i < 4; ++i) pr[i] = __shfl_xor(v[0][n][i], 16);
;                             if (fq < 2) {
;                                 const f32x4 cs = *(const f32x4*)(rope + s * 16 + 4 * n), sn = *(const f32x4*)(rope + s * 16 + 8 + 4 * n);
;                                 v[0][n] = (fq == 0) ? (v[0][n] * cs - pr * sn) : (v[0][n] * cs + pr * sn);
;                             }
;                         }
;                     }
;                     bf16_t* dst;
;                     if (pn < 2) dst = Q + (size_t)row * 512 + (4 * pn + wc) * 64 + 8 * fq;
;                     else { const int b = row >> 11, sq = row & (SEQ - 1); dst = KV + (size_t)slot * KV_SLOT + ((size_t)((b * 2 + gidx) * SEQ + sq)) * 64 + 8 * fq; }
; #pragma unroll
;                     for (int bj = 0; bj < 2; ++bj) store8(dst + 32 * bj, v[bj][0] * scale, v[bj][1] * scale);
.LBB0_441:
	s_mov_b32 s70, s64
	s_mov_b32 s71, s64
	v_lshl_add_u64 v[82:83], v[84:85], 0, v[156:157]
	v_pk_mul_f32 v[80:81], s[70:71], v[80:81]
	v_pk_mul_f32 v[78:79], s[64:65], v[78:79]
	v_pk_mul_f32 v[84:85], s[70:71], v[76:77]
	v_pk_mul_f32 v[76:77], s[64:65], v[74:75]
	v_cvt_pk_bf16_f32 v74, v78, v79
	v_cvt_pk_bf16_f32 v75, v80, v81
	v_cvt_pk_bf16_f32 v76, v76, v77
	v_cvt_pk_bf16_f32 v77, v84, v85
	v_pk_mul_f32 v[70:71], s[64:65], v[70:71]
	global_store_dwordx4 v[82:83], v[74:77], off
	v_pk_mul_f32 v[72:73], s[70:71], v[72:73]
	s_addk_i32 s28, 0x80
	v_pk_mul_f32 v[74:75], s[70:71], v[68:69]
	v_pk_mul_f32 v[68:69], s[64:65], v[66:67]
	v_cvt_pk_bf16_f32 v66, v70, v71
	v_fmamk_f32 v70, v194, 0x3a800000, v187
	v_rsq_f32_e32 v70, v70
	v_cvt_pk_bf16_f32 v67, v72, v73
	v_cvt_pk_bf16_f32 v68, v68, v69
	v_cvt_pk_bf16_f32 v69, v74, v75
	global_store_dwordx4 v[82:83], v[66:69], off offset:64
	v_pk_mul_f32 v[64:65], v[70:71], v[64:65] op_sel_hi:[0,1]
	v_pk_mul_f32 v[62:63], v[70:71], v[62:63] op_sel_hi:[0,1]
	v_or_b32_e32 v66, s28, v147
	v_pk_mul_f32 v[60:61], v[70:71], v[60:61] op_sel_hi:[0,1]
	v_pk_mul_f32 v[58:59], v[70:71], v[58:59] op_sel_hi:[0,1]
	v_pk_mul_f32 v[56:57], v[70:71], v[56:57] op_sel_hi:[0,1]
	v_pk_mul_f32 v[54:55], v[70:71], v[54:55] op_sel_hi:[0,1]
	v_pk_mul_f32 v[52:53], v[70:71], v[52:53] op_sel_hi:[0,1]
	s_and_b64 vcc, exec, s[10:11]
	v_pk_mul_f32 v[50:51], v[70:71], v[50:51] op_sel_hi:[0,1]
	s_cbranch_vccnz .LBB0_447
	v_lshlrev_b32_e32 v222, 6, v66
	v_and_b32_e32 v222, 0x1ffc0, v222
	global_load_dwordx4 v[206:209], v222, s[40:41] offset:32
	global_load_dwordx4 v[210:213], v222, s[40:41]
	global_load_dwordx4 v[214:217], v222, s[40:41] offset:48
	global_load_dwordx4 v[218:221], v222, s[40:41] offset:16
	v_pk_mul_f32 v[68:69], v[64:65], v[64:65]
	v_pk_mul_f32 v[70:71], v[62:63], v[62:63]
	v_mul_f32_e32 v67, v50, v50
	v_pk_mov_b32 v[72:73], v[70:71], v[68:69] op_sel:[1,0]
	v_mov_b32_e32 v71, v69
	v_pk_add_f32 v[68:69], v[72:73], v[70:71]
	v_pk_mul_f32 v[70:71], v[60:61], v[60:61]
	v_pk_mul_f32 v[72:73], v[58:59], v[58:59]
	v_pk_add_f32 v[68:69], v[68:69], v[68:69] op_sel:[0,1] op_sel_hi:[1,0]
	v_pk_mov_b32 v[74:75], v[72:73], v[70:71] op_sel:[1,0]
	v_mov_b32_e32 v73, v71
	v_pk_add_f32 v[70:71], v[74:75], v[72:73]
	v_mul_f32_e32 v72, v51, v51
	v_pk_add_f32 v[70:71], v[70:71], v[70:71] op_sel:[0,1] op_sel_hi:[1,0]
	v_mov_b32_e32 v69, v67
	v_mov_b32_e32 v71, v72
	v_pk_add_f32 v[68:69], v[68:69], v[70:71]
	v_mul_f32_e32 v70, v55, v55
	v_mul_f32_e32 v73, v52, v52
	v_pk_fma_f32 v[70:71], v[54:55], v[54:55], v[70:71] op_sel_hi:[1,1,0]
	v_mul_f32_e32 v72, v57, v57
	v_mul_f32_e32 v74, v53, v53
	v_mov_b32_e32 v71, v73
	v_pk_fma_f32 v[72:73], v[56:57], v[56:57], v[72:73] op_sel_hi:[1,1,0]
	v_xor_b32_e32 v67, 16, v190
	v_mov_b32_e32 v73, v74
	v_pk_add_f32 v[70:71], v[70:71], v[72:73]
	v_mov_b32_e32 v73, v157
	v_pk_add_f32 v[68:69], v[68:69], v[70:71]
	s_nop 0
	v_add_f32_e32 v68, v68, v69
	v_and_b32_e32 v69, 64, v190
	v_add_u32_e32 v69, 64, v69
	v_cmp_lt_i32_e32 vcc, v67, v69
	s_nop 1
	v_cndmask_b32_e32 v67, v190, v67, vcc
	v_lshlrev_b32_e32 v67, 2, v67
	v_mov_b32_e32 v70, v68
	s_nop 1
	v_permlane16_swap_b32_e32 v70, v68
	v_add_f32_e32 v68, v68, v70
	v_xor_b32_e32 v70, 32, v190
	v_cmp_lt_i32_e32 vcc, v70, v69
	s_nop 1
	v_cndmask_b32_e32 v69, v190, v70, vcc
	v_lshlrev_b32_e32 v69, 2, v69
	v_mov_b32_e32 v69, v68
	s_nop 1
	v_permlane32_swap_b32_e32 v69, v68
	v_add_f32_e32 v68, v68, v69
	v_fmamk_f32 v68, v68, 0x3c800000, v187
	v_rsq_f32_e32 v68, v68
	s_nop 0
	v_pk_mul_f32 v[62:63], v[62:63], v[68:69] op_sel_hi:[1,0]
	v_pk_mul_f32 v[64:65], v[64:65], v[68:69] op_sel_hi:[1,0]
	v_pk_mul_f32 v[62:63], v[142:143], v[62:63]
	v_pk_mul_f32 v[64:65], v[144:145], v[64:65]
	ds_bpermute_b32 v70, v67, v62
	ds_bpermute_b32 v71, v67, v63
	ds_bpermute_b32 v74, v67, v64
	ds_bpermute_b32 v75, v67, v65
	v_lshlrev_b32_e32 v69, 6, v66
	v_and_b32_e32 v72, 0x1f3c0, v69
	v_lshl_add_u64 v[72:73], s[40:41], 0, v[72:73]
	s_and_saveexec_b64 s[70:71], s[4:5]
	s_cbranch_execz .LBB0_444
	s_waitcnt vmcnt(2)
	v_mov_b64_e32 v[76:77], v[206:207]
	v_mov_b64_e32 v[78:79], v[208:209]
	v_mov_b64_e32 v[80:81], v[210:211]
	v_mov_b64_e32 v[82:83], v[212:213]
	s_waitcnt lgkmcnt(0)
	v_pk_mul_f32 v[74:75], v[78:79], v[74:75]
	v_pk_mul_f32 v[70:71], v[76:77], v[70:71]
	v_xor_b32_e32 v69, 0x80000000, v74
	v_xor_b32_e32 v76, 0x80000000, v75
	v_xor_b32_e32 v77, 0x80000000, v70
	v_xor_b32_e32 v78, 0x80000000, v71
	v_cndmask_b32_e64 v75, v75, v76, s[6:7]
	v_cndmask_b32_e64 v74, v74, v69, s[6:7]
	v_cndmask_b32_e64 v71, v71, v78, s[6:7]
	v_cndmask_b32_e64 v70, v70, v77, s[6:7]
	v_pk_fma_f32 v[64:65], v[64:65], v[82:83], v[74:75]
	v_pk_fma_f32 v[62:63], v[62:63], v[80:81], v[70:71]

;     DI void operator()(Acc& acc, const pg8::Unit& u, int wr, int wc, int fr, int fq, const Pre& pr) const {
;     ...
;                         float ss = 0.f;
; #pragma unroll
;                         for (int bj = 0; bj < 2; ++bj)
; #pragma unroll
;                             for (int n = 0; n < 2; ++n) ss += (v[bj][n][0] * v[bj][n][0] + v[bj][n][1] * v[bj][n][1]) + (v[bj][n][2] * v[bj][n][2] + v[bj][n][3] * v[bj][n][3]);
;                         ss += __shfl_xor(ss, 16); ss += __shfl_xor(ss, 32);
;                         const float hr = __builtin_amdgcn_rsqf(ss * (1.0f / 64.0f) + NORM_EPS);
; #pragma unroll
;                         for (int bj = 0; bj < 2; ++bj)
; #pragma unroll
;                             for (int n = 0; n < 2; ++n) v[bj][n] = v[bj][n] * hr * gn[bj][n];
;                         const int s = row & (SEQ - 1);
; #pragma unroll
;                         for (int n = 0; n < 2; ++n) {
;                             f32x4 pr;
; #pragma unroll
;                             for (int i = 0; i < 4; ++i) pr[i] = __shfl_xor(v[0][n][i], 16);
;                             if (fq < 2) {
;                                 const f32x4 cs = *(const f32x4*)(rope + s * 16 + 4 * n), sn = *(const f32x4*)(rope + s * 16 + 8 + 4 * n);
;                                 v[0][n] = (fq == 0) ? (v[0][n] * cs - pr * sn) : (v[0][n] * cs + pr * sn);
;                             }
;                         }
.LBB0_466:
	v_lshlrev_b32_e32 v222, 6, v98
	v_and_b32_e32 v222, 0x1ffc0, v222
	global_load_dwordx4 v[206:209], v222, s[40:41] offset:32
	global_load_dwordx4 v[210:213], v222, s[40:41]
	global_load_dwordx4 v[214:217], v222, s[40:41] offset:48
	global_load_dwordx4 v[218:221], v222, s[40:41] offset:16
	v_pk_mul_f32 v[100:101], v[96:97], v[96:97]
	v_pk_mul_f32 v[102:103], v[94:95], v[94:95]
	v_mul_f32_e32 v99, v82, v82
	v_pk_mov_b32 v[104:105], v[102:103], v[100:101] op_sel:[1,0]
	v_mov_b32_e32 v103, v101
	v_pk_add_f32 v[100:101], v[104:105], v[102:103]
	v_pk_mul_f32 v[102:103], v[92:93], v[92:93]
	v_pk_mul_f32 v[104:105], v[90:91], v[90:91]
	v_pk_add_f32 v[100:101], v[100:101], v[100:101] op_sel:[0,1] op_sel_hi:[1,0]
	v_pk_mov_b32 v[106:107], v[104:105], v[102:103] op_sel:[1,0]
	v_mov_b32_e32 v105, v103
	v_pk_add_f32 v[102:103], v[106:107], v[104:105]
	v_mul_f32_e32 v104, v83, v83
	v_pk_add_f32 v[102:103], v[102:103], v[102:103] op_sel:[0,1] op_sel_hi:[1,0]
	v_mov_b32_e32 v101, v99
	v_mov_b32_e32 v103, v104
	v_pk_add_f32 v[100:101], v[100:101], v[102:103]
	v_mul_f32_e32 v102, v87, v87
	v_mul_f32_e32 v105, v84, v84
	v_pk_fma_f32 v[102:103], v[86:87], v[86:87], v[102:103] op_sel_hi:[1,1,0]
	v_mul_f32_e32 v104, v89, v89
	v_mul_f32_e32 v106, v85, v85
	v_mov_b32_e32 v103, v105
	v_pk_fma_f32 v[104:105], v[88:89], v[88:89], v[104:105] op_sel_hi:[1,1,0]
	v_xor_b32_e32 v99, 16, v190
	v_mov_b32_e32 v105, v106
	v_pk_add_f32 v[102:103], v[102:103], v[104:105]
	v_mov_b32_e32 v105, v157
	v_pk_add_f32 v[100:101], v[100:101], v[102:103]
	s_nop 0
	v_add_f32_e32 v100, v100, v101
	v_and_b32_e32 v101, 64, v190
	v_add_u32_e32 v101, 64, v101
	v_cmp_lt_i32_e32 vcc, v99, v101
	s_nop 1
	v_cndmask_b32_e32 v99, v190, v99, vcc
	v_lshlrev_b32_e32 v99, 2, v99
	v_mov_b32_e32 v102, v100
	s_nop 1
	v_permlane16_swap_b32_e32 v102, v100
	v_add_f32_e32 v100, v100, v102
	v_xor_b32_e32 v102, 32, v190
	v_cmp_lt_i32_e32 vcc, v102, v101
	s_nop 1
	v_cndmask_b32_e32 v101, v190, v102, vcc
	v_lshlrev_b32_e32 v101, 2, v101
	v_mov_b32_e32 v101, v100
	s_nop 1
	v_permlane32_swap_b32_e32 v101, v100
	v_add_f32_e32 v100, v100, v101
	v_fmamk_f32 v100, v100, 0x3c800000, v187
	v_rsq_f32_e32 v100, v100
	s_nop 0
	v_pk_mul_f32 v[94:95], v[94:95], v[100:101] op_sel_hi:[1,0]
	v_pk_mul_f32 v[96:97], v[96:97], v[100:101] op_sel_hi:[1,0]
	v_pk_mul_f32 v[94:95], v[142:143], v[94:95]
	v_pk_mul_f32 v[96:97], v[144:145], v[96:97]
	ds_bpermute_b32 v102, v99, v94
	ds_bpermute_b32 v103, v99, v95
	ds_bpermute_b32 v106, v99, v96
	ds_bpermute_b32 v107, v99, v97
	v_lshlrev_b32_e32 v101, 6, v98
	v_and_b32_e32 v104, 0x1fbc0, v101
	v_lshl_add_u64 v[104:105], s[40:41], 0, v[104:105]
	s_and_saveexec_b64 s[70:71], s[4:5]
	s_cbranch_execz .LBB0_468
	s_waitcnt vmcnt(2)
	v_mov_b64_e32 v[108:109], v[206:207]
	v_mov_b64_e32 v[110:111], v[208:209]
	v_mov_b64_e32 v[112:113], v[210:211]
	v_mov_b64_e32 v[114:115], v[212:213]
	s_waitcnt lgkmcnt(0)
	v_pk_mul_f32 v[106:107], v[110:111], v[106:107]
	v_pk_mul_f32 v[102:103], v[108:109], v[102:103]
	v_xor_b32_e32 v101, 0x80000000, v106
	v_xor_b32_e32 v108, 0x80000000, v107
	v_xor_b32_e32 v109, 0x80000000, v102
	v_xor_b32_e32 v110, 0x80000000, v103
	v_cndmask_b32_e64 v107, v107, v108, s[6:7]
	v_cndmask_b32_e64 v106, v106, v101, s[6:7]
	v_cndmask_b32_e64 v103, v103, v110, s[6:7]
	v_cndmask_b32_e64 v102, v102, v109, s[6:7]
	v_pk_fma_f32 v[96:97], v[96:97], v[114:115], v[106:107]
	v_pk_fma_f32 v[94:95], v[94:95], v[112:113], v[102:103]

;     DI void operator()(Acc& acc, const pg8::Unit& u, int wr, int wc, int fr, int fq, const Pre& pr) const {
;     ...
;                         float ss = 0.f;
; #pragma unroll
;                         for (int bj = 0; bj < 2; ++bj)
; #pragma unroll
;                             for (int n = 0; n < 2; ++n) ss += (v[bj][n][0] * v[bj][n][0] + v[bj][n][1] * v[bj][n][1]) + (v[bj][n][2] * v[bj][n][2] + v[bj][n][3] * v[bj][n][3]);
;                         ss += __shfl_xor(ss, 16); ss += __shfl_xor(ss, 32);
;                         const float hr = __builtin_amdgcn_rsqf(ss * (1.0f / 64.0f) + NORM_EPS);
; #pragma unroll
;                         for (int bj = 0; bj < 2; ++bj)
; #pragma unroll
;                             for (int n = 0; n < 2; ++n) v[bj][n] = v[bj][n] * hr * gn[bj][n];
;                         const int s = row & (SEQ - 1);
; #pragma unroll
;                         for (int n = 0; n < 2; ++n) {
;                             f32x4 pr;
; #pragma unroll
;                             for (int i = 0; i < 4; ++i) pr[i] = __shfl_xor(v[0][n][i], 16);
;                             if (fq < 2) {
;                                 const f32x4 cs = *(const f32x4*)(rope + s * 16 + 4 * n), sn = *(const f32x4*)(rope + s * 16 + 8 + 4 * n);
;                                 v[0][n] = (fq == 0) ? (v[0][n] * cs - pr * sn) : (v[0][n] * cs + pr * sn);
;                             }
;                         }
.LBB0_472:
	v_lshlrev_b32_e32 v222, 6, v82
	v_and_b32_e32 v222, 0x1ffc0, v222
	global_load_dwordx4 v[206:209], v222, s[40:41] offset:32
	global_load_dwordx4 v[210:213], v222, s[40:41]
	global_load_dwordx4 v[214:217], v222, s[40:41] offset:48
	global_load_dwordx4 v[218:221], v222, s[40:41] offset:16
	v_pk_mul_f32 v[84:85], v[80:81], v[80:81]
	v_pk_mul_f32 v[86:87], v[78:79], v[78:79]
	v_mul_f32_e32 v83, v66, v66
	v_pk_mov_b32 v[88:89], v[86:87], v[84:85] op_sel:[1,0]
	v_mov_b32_e32 v87, v85
	v_pk_add_f32 v[84:85], v[88:89], v[86:87]
	v_pk_mul_f32 v[86:87], v[76:77], v[76:77]
	v_pk_mul_f32 v[88:89], v[74:75], v[74:75]
	v_pk_add_f32 v[84:85], v[84:85], v[84:85] op_sel:[0,1] op_sel_hi:[1,0]
	v_pk_mov_b32 v[90:91], v[88:89], v[86:87] op_sel:[1,0]
	v_mov_b32_e32 v89, v87
	v_pk_add_f32 v[86:87], v[90:91], v[88:89]
	v_mul_f32_e32 v88, v67, v67
	v_pk_add_f32 v[86:87], v[86:87], v[86:87] op_sel:[0,1] op_sel_hi:[1,0]
	v_mov_b32_e32 v85, v83
	v_mov_b32_e32 v87, v88
	v_pk_add_f32 v[84:85], v[84:85], v[86:87]
	v_mul_f32_e32 v86, v71, v71
	v_mul_f32_e32 v89, v68, v68
	v_pk_fma_f32 v[86:87], v[70:71], v[70:71], v[86:87] op_sel_hi:[1,1,0]
	v_mul_f32_e32 v88, v73, v73
	v_mul_f32_e32 v90, v69, v69
	v_mov_b32_e32 v87, v89
	v_pk_fma_f32 v[88:89], v[72:73], v[72:73], v[88:89] op_sel_hi:[1,1,0]
	v_xor_b32_e32 v83, 16, v190
	v_mov_b32_e32 v89, v90
	v_pk_add_f32 v[86:87], v[86:87], v[88:89]
	v_mov_b32_e32 v89, v157
	v_pk_add_f32 v[84:85], v[84:85], v[86:87]
	s_nop 0
	v_add_f32_e32 v84, v84, v85
	v_and_b32_e32 v85, 64, v190
	v_add_u32_e32 v85, 64, v85
	v_cmp_lt_i32_e32 vcc, v83, v85
	s_nop 1
	v_cndmask_b32_e32 v83, v190, v83, vcc
	v_lshlrev_b32_e32 v83, 2, v83
	v_mov_b32_e32 v86, v84
	s_nop 1
	v_permlane16_swap_b32_e32 v86, v84
	v_add_f32_e32 v84, v84, v86
	v_xor_b32_e32 v86, 32, v190
	v_cmp_lt_i32_e32 vcc, v86, v85
	s_nop 1
	v_cndmask_b32_e32 v85, v190, v86, vcc
	v_lshlrev_b32_e32 v85, 2, v85
	v_mov_b32_e32 v85, v84
	s_nop 1
	v_permlane32_swap_b32_e32 v85, v84
	v_add_f32_e32 v84, v84, v85
	v_fmamk_f32 v84, v84, 0x3c800000, v187
	v_rsq_f32_e32 v84, v84
	s_nop 0
	v_pk_mul_f32 v[78:79], v[78:79], v[84:85] op_sel_hi:[1,0]
	v_pk_mul_f32 v[80:81], v[80:81], v[84:85] op_sel_hi:[1,0]
	v_pk_mul_f32 v[78:79], v[142:143], v[78:79]
	v_pk_mul_f32 v[80:81], v[144:145], v[80:81]
	ds_bpermute_b32 v86, v83, v78
	ds_bpermute_b32 v87, v83, v79
	ds_bpermute_b32 v90, v83, v80
	ds_bpermute_b32 v91, v83, v81
	v_lshlrev_b32_e32 v85, 6, v82
	v_and_b32_e32 v88, 0x1ffc0, v85
	v_lshl_add_u64 v[88:89], s[40:41], 0, v[88:89]
	s_and_saveexec_b64 s[70:71], s[4:5]
	s_cbranch_execz .LBB0_474
	s_waitcnt vmcnt(2)
	v_mov_b64_e32 v[92:93], v[206:207]
	v_mov_b64_e32 v[94:95], v[208:209]
	v_mov_b64_e32 v[96:97], v[210:211]
	v_mov_b64_e32 v[98:99], v[212:213]
	s_waitcnt lgkmcnt(0)
	v_pk_mul_f32 v[90:91], v[94:95], v[90:91]
	v_pk_mul_f32 v[86:87], v[92:93], v[86:87]
	v_xor_b32_e32 v85, 0x80000000, v90
	v_xor_b32_e32 v92, 0x80000000, v91
	v_xor_b32_e32 v93, 0x80000000, v86
	v_xor_b32_e32 v94, 0x80000000, v87
	v_cndmask_b32_e64 v91, v91, v92, s[6:7]
	v_cndmask_b32_e64 v90, v90, v85, s[6:7]
	v_cndmask_b32_e64 v87, v87, v94, s[6:7]
	v_cndmask_b32_e64 v86, v86, v93, s[6:7]
	v_pk_fma_f32 v[80:81], v[80:81], v[98:99], v[90:91]
	v_pk_fma_f32 v[78:79], v[78:79], v[96:97], v[86:87]

;     DI void operator()(Acc& acc, const pg8::Unit& u, int wr, int wc, int fr, int fq, const Pre& pr) const {
;     ...
;                         float ss = 0.f;
; #pragma unroll
;                         for (int bj = 0; bj < 2; ++bj)
; #pragma unroll
;                             for (int n = 0; n < 2; ++n) ss += (v[bj][n][0] * v[bj][n][0] + v[bj][n][1] * v[bj][n][1]) + (v[bj][n][2] * v[bj][n][2] + v[bj][n][3] * v[bj][n][3]);
;                         ss += __shfl_xor(ss, 16); ss += __shfl_xor(ss, 32);
;                         const float hr = __builtin_amdgcn_rsqf(ss * (1.0f / 64.0f) + NORM_EPS);
; #pragma unroll
;                         for (int bj = 0; bj < 2; ++bj)
; #pragma unroll
;                             for (int n = 0; n < 2; ++n) v[bj][n] = v[bj][n] * hr * gn[bj][n];
;                         const int s = row & (SEQ - 1);
; #pragma unroll
;                         for (int n = 0; n < 2; ++n) {
;                             f32x4 pr;
; #pragma unroll
;                             for (int i = 0; i < 4; ++i) pr[i] = __shfl_xor(v[0][n][i], 16);
;                             if (fq < 2) {
;                                 const f32x4 cs = *(const f32x4*)(rope + s * 16 + 4 * n), sn = *(const f32x4*)(rope + s * 16 + 8 + 4 * n);
;                                 v[0][n] = (fq == 0) ? (v[0][n] * cs - pr * sn) : (v[0][n] * cs + pr * sn);
;                             }
;                         }
.LBB0_478:
	v_lshlrev_b32_e32 v222, 6, v50
	v_and_b32_e32 v222, 0x1ffc0, v222
	global_load_dwordx4 v[206:209], v222, s[40:41] offset:32
	global_load_dwordx4 v[210:213], v222, s[40:41]
	global_load_dwordx4 v[214:217], v222, s[40:41] offset:48
	global_load_dwordx4 v[218:221], v222, s[40:41] offset:16
	v_pk_mul_f32 v[52:53], v[48:49], v[48:49]
	v_pk_mul_f32 v[54:55], v[46:47], v[46:47]
	v_mul_f32_e32 v51, v34, v34
	v_pk_mov_b32 v[56:57], v[54:55], v[52:53] op_sel:[1,0]
	v_mov_b32_e32 v55, v53
	v_pk_add_f32 v[52:53], v[56:57], v[54:55]
	v_pk_mul_f32 v[54:55], v[44:45], v[44:45]
	v_pk_mul_f32 v[56:57], v[42:43], v[42:43]
	v_pk_add_f32 v[52:53], v[52:53], v[52:53] op_sel:[0,1] op_sel_hi:[1,0]
	v_pk_mov_b32 v[58:59], v[56:57], v[54:55] op_sel:[1,0]
	v_mov_b32_e32 v57, v55
	v_pk_add_f32 v[54:55], v[58:59], v[56:57]
	v_mul_f32_e32 v56, v35, v35
	v_pk_add_f32 v[54:55], v[54:55], v[54:55] op_sel:[0,1] op_sel_hi:[1,0]
	v_mov_b32_e32 v53, v51
	v_mov_b32_e32 v55, v56
	v_pk_add_f32 v[52:53], v[52:53], v[54:55]
	v_mul_f32_e32 v54, v39, v39
	v_mul_f32_e32 v57, v36, v36
	v_pk_fma_f32 v[54:55], v[38:39], v[38:39], v[54:55] op_sel_hi:[1,1,0]
	v_mul_f32_e32 v56, v41, v41
	v_mul_f32_e32 v58, v37, v37
	v_mov_b32_e32 v55, v57
	v_pk_fma_f32 v[56:57], v[40:41], v[40:41], v[56:57] op_sel_hi:[1,1,0]
	v_xor_b32_e32 v51, 16, v190
	v_mov_b32_e32 v57, v58
	v_pk_add_f32 v[54:55], v[54:55], v[56:57]
	v_mov_b32_e32 v57, v157
	v_pk_add_f32 v[52:53], v[52:53], v[54:55]
	s_nop 0
	v_add_f32_e32 v52, v52, v53
	v_and_b32_e32 v53, 64, v190
	v_add_u32_e32 v53, 64, v53
	v_cmp_lt_i32_e32 vcc, v51, v53
	s_nop 1
	v_cndmask_b32_e32 v51, v190, v51, vcc
	v_lshlrev_b32_e32 v51, 2, v51
	v_mov_b32_e32 v54, v52
	s_nop 1
	v_permlane16_swap_b32_e32 v54, v52
	v_add_f32_e32 v52, v52, v54
	v_xor_b32_e32 v54, 32, v190
	v_cmp_lt_i32_e32 vcc, v54, v53
	s_nop 1
	v_cndmask_b32_e32 v53, v190, v54, vcc
	v_lshlrev_b32_e32 v53, 2, v53
	v_mov_b32_e32 v53, v52
	s_nop 1
	v_permlane32_swap_b32_e32 v53, v52
	v_add_f32_e32 v52, v52, v53
	v_fmamk_f32 v52, v52, 0x3c800000, v187
	v_rsq_f32_e32 v52, v52
	s_nop 0
	v_pk_mul_f32 v[46:47], v[46:47], v[52:53] op_sel_hi:[1,0]
	v_pk_mul_f32 v[48:49], v[48:49], v[52:53] op_sel_hi:[1,0]
	v_pk_mul_f32 v[46:47], v[142:143], v[46:47]
	v_pk_mul_f32 v[48:49], v[144:145], v[48:49]
	ds_bpermute_b32 v54, v51, v46
	ds_bpermute_b32 v55, v51, v47
	ds_bpermute_b32 v58, v51, v48
	ds_bpermute_b32 v59, v51, v49
	v_lshlrev_b32_e32 v53, 6, v50
	v_and_b32_e32 v56, 0x1ffc0, v53
	v_lshl_add_u64 v[56:57], s[40:41], 0, v[56:57]
	s_and_saveexec_b64 s[70:71], s[4:5]
	s_cbranch_execz .LBB0_480
	s_waitcnt vmcnt(2)
	v_mov_b64_e32 v[60:61], v[206:207]
	v_mov_b64_e32 v[62:63], v[208:209]
	v_mov_b64_e32 v[68:69], v[210:211]
	v_mov_b64_e32 v[70:71], v[212:213]
	s_waitcnt lgkmcnt(0)
	v_pk_mul_f32 v[58:59], v[62:63], v[58:59]
	v_pk_mul_f32 v[54:55], v[60:61], v[54:55]
	v_xor_b32_e32 v53, 0x80000000, v58
	v_xor_b32_e32 v60, 0x80000000, v59
	v_xor_b32_e32 v61, 0x80000000, v54
	v_xor_b32_e32 v62, 0x80000000, v55
	v_cndmask_b32_e64 v59, v59, v60, s[6:7]
	v_cndmask_b32_e64 v58, v58, v53, s[6:7]
	v_cndmask_b32_e64 v55, v55, v62, s[6:7]
	v_cndmask_b32_e64 v54, v54, v61, s[6:7]
	v_pk_fma_f32 v[48:49], v[48:49], v[70:71], v[58:59]
	v_pk_fma_f32 v[46:47], v[46:47], v[68:69], v[54:55]

;     DI void operator()(Acc& acc, const pg8::Unit& u, int wr, int wc, int fr, int fq, const Pre& pr) const {
;     ...
;                         float ss = 0.f;
; #pragma unroll
;                         for (int bj = 0; bj < 2; ++bj)
; #pragma unroll
;                             for (int n = 0; n < 2; ++n) ss += (v[bj][n][0] * v[bj][n][0] + v[bj][n][1] * v[bj][n][1]) + (v[bj][n][2] * v[bj][n][2] + v[bj][n][3] * v[bj][n][3]);
;                         ss += __shfl_xor(ss, 16); ss += __shfl_xor(ss, 32);
;                         const float hr = __builtin_amdgcn_rsqf(ss * (1.0f / 64.0f) + NORM_EPS);
; #pragma unroll
;                         for (int bj = 0; bj < 2; ++bj)
; #pragma unroll
;                             for (int n = 0; n < 2; ++n) v[bj][n] = v[bj][n] * hr * gn[bj][n];
;                         const int s = row & (SEQ - 1);
; #pragma unroll
;                         for (int n = 0; n < 2; ++n) {
;                             f32x4 pr;
; #pragma unroll
;                             for (int i = 0; i < 4; ++i) pr[i] = __shfl_xor(v[0][n][i], 16);
;                             if (fq < 2) {
;                                 const f32x4 cs = *(const f32x4*)(rope + s * 16 + 4 * n), sn = *(const f32x4*)(rope + s * 16 + 8 + 4 * n);
;                                 v[0][n] = (fq == 0) ? (v[0][n] * cs - pr * sn) : (v[0][n] * cs + pr * sn);
;                             }
;                         }
.LBB0_484:
	v_lshlrev_b32_e32 v222, 6, v34
	v_and_b32_e32 v222, 0x1ffc0, v222
	global_load_dwordx4 v[206:209], v222, s[40:41] offset:32
	global_load_dwordx4 v[210:213], v222, s[40:41]
	global_load_dwordx4 v[214:217], v222, s[40:41] offset:48
	global_load_dwordx4 v[218:221], v222, s[40:41] offset:16
	v_pk_mul_f32 v[36:37], v[32:33], v[32:33]
	v_pk_mul_f32 v[38:39], v[30:31], v[30:31]
	v_mul_f32_e32 v35, v18, v18
	v_pk_mov_b32 v[40:41], v[38:39], v[36:37] op_sel:[1,0]
	v_mov_b32_e32 v39, v37
	v_pk_add_f32 v[36:37], v[40:41], v[38:39]
	v_pk_mul_f32 v[38:39], v[28:29], v[28:29]
	v_pk_mul_f32 v[40:41], v[26:27], v[26:27]
	v_pk_add_f32 v[36:37], v[36:37], v[36:37] op_sel:[0,1] op_sel_hi:[1,0]
	v_pk_mov_b32 v[42:43], v[40:41], v[38:39] op_sel:[1,0]
	v_mov_b32_e32 v41, v39
	v_pk_add_f32 v[38:39], v[42:43], v[40:41]
	v_mul_f32_e32 v40, v19, v19
	v_pk_add_f32 v[38:39], v[38:39], v[38:39] op_sel:[0,1] op_sel_hi:[1,0]
	v_mov_b32_e32 v37, v35
	v_mov_b32_e32 v39, v40
	v_pk_add_f32 v[36:37], v[36:37], v[38:39]
	v_mul_f32_e32 v38, v23, v23
	v_mul_f32_e32 v41, v20, v20
	v_pk_fma_f32 v[38:39], v[22:23], v[22:23], v[38:39] op_sel_hi:[1,1,0]
	v_mul_f32_e32 v40, v25, v25
	v_mul_f32_e32 v42, v21, v21
	v_mov_b32_e32 v39, v41
	v_pk_fma_f32 v[40:41], v[24:25], v[24:25], v[40:41] op_sel_hi:[1,1,0]
	v_xor_b32_e32 v35, 16, v190
	v_mov_b32_e32 v41, v42
	v_pk_add_f32 v[38:39], v[38:39], v[40:41]
	v_mov_b32_e32 v41, v157
	v_pk_add_f32 v[36:37], v[36:37], v[38:39]
	s_nop 0
	v_add_f32_e32 v36, v36, v37
	v_and_b32_e32 v37, 64, v190
	v_add_u32_e32 v37, 64, v37
	v_cmp_lt_i32_e32 vcc, v35, v37
	s_nop 1
	v_cndmask_b32_e32 v35, v190, v35, vcc
	v_lshlrev_b32_e32 v35, 2, v35
	v_mov_b32_e32 v38, v36
	s_nop 1
	v_permlane16_swap_b32_e32 v38, v36
	v_add_f32_e32 v36, v36, v38
	v_xor_b32_e32 v38, 32, v190
	v_cmp_lt_i32_e32 vcc, v38, v37
	s_nop 1
	v_cndmask_b32_e32 v37, v190, v38, vcc
	v_lshlrev_b32_e32 v37, 2, v37
	v_mov_b32_e32 v37, v36
	s_nop 1
	v_permlane32_swap_b32_e32 v37, v36
	v_add_f32_e32 v36, v36, v37
	v_fmamk_f32 v36, v36, 0x3c800000, v187
	v_rsq_f32_e32 v36, v36
	s_nop 0
	v_pk_mul_f32 v[30:31], v[30:31], v[36:37] op_sel_hi:[1,0]
	v_pk_mul_f32 v[32:33], v[32:33], v[36:37] op_sel_hi:[1,0]
	v_pk_mul_f32 v[30:31], v[142:143], v[30:31]
	v_pk_mul_f32 v[32:33], v[144:145], v[32:33]
	ds_bpermute_b32 v38, v35, v30
	ds_bpermute_b32 v39, v35, v31
	ds_bpermute_b32 v42, v35, v32
	ds_bpermute_b32 v43, v35, v33
	v_lshlrev_b32_e32 v37, 6, v34
	v_and_b32_e32 v40, 0x1ffc0, v37
	v_lshl_add_u64 v[40:41], s[40:41], 0, v[40:41]
	s_and_saveexec_b64 s[70:71], s[4:5]
	s_cbranch_execz .LBB0_486
	s_waitcnt vmcnt(2)
	v_mov_b64_e32 v[44:45], v[206:207]
	v_mov_b64_e32 v[46:47], v[208:209]
	v_mov_b64_e32 v[48:49], v[210:211]
	v_mov_b64_e32 v[50:51], v[212:213]
	s_waitcnt lgkmcnt(0)
	v_pk_mul_f32 v[42:43], v[46:47], v[42:43]
	v_pk_mul_f32 v[38:39], v[44:45], v[38:39]
	v_xor_b32_e32 v37, 0x80000000, v42
	v_xor_b32_e32 v44, 0x80000000, v43
	v_xor_b32_e32 v45, 0x80000000, v38
	v_xor_b32_e32 v46, 0x80000000, v39
	v_cndmask_b32_e64 v43, v43, v44, s[6:7]
	v_cndmask_b32_e64 v42, v42, v37, s[6:7]
	v_cndmask_b32_e64 v39, v39, v46, s[6:7]
	v_cndmask_b32_e64 v38, v38, v45, s[6:7]
	v_pk_fma_f32 v[32:33], v[32:33], v[50:51], v[42:43]
	v_pk_fma_f32 v[30:31], v[30:31], v[48:49], v[38:39]

;     DI void operator()(Acc& acc, const pg8::Unit& u, int wr, int wc, int fr, int fq, const Pre& pr) const {
;     ...
;                         float ss = 0.f;
; #pragma unroll
;                         for (int bj = 0; bj < 2; ++bj)
; #pragma unroll
;                             for (int n = 0; n < 2; ++n) ss += (v[bj][n][0] * v[bj][n][0] + v[bj][n][1] * v[bj][n][1]) + (v[bj][n][2] * v[bj][n][2] + v[bj][n][3] * v[bj][n][3]);
;                         ss += __shfl_xor(ss, 16); ss += __shfl_xor(ss, 32);
;                         const float hr = __builtin_amdgcn_rsqf(ss * (1.0f / 64.0f) + NORM_EPS);
; #pragma unroll
;                         for (int bj = 0; bj < 2; ++bj)
; #pragma unroll
;                             for (int n = 0; n < 2; ++n) v[bj][n] = v[bj][n] * hr * gn[bj][n];
;                         const int s = row & (SEQ - 1);
; #pragma unroll
;                         for (int n = 0; n < 2; ++n) {
;                             f32x4 pr;
; #pragma unroll
;                             for (int i = 0; i < 4; ++i) pr[i] = __shfl_xor(v[0][n][i], 16);
;                             if (fq < 2) {
;                                 const f32x4 cs = *(const f32x4*)(rope + s * 16 + 4 * n), sn = *(const f32x4*)(rope + s * 16 + 8 + 4 * n);
;                                 v[0][n] = (fq == 0) ? (v[0][n] * cs - pr * sn) : (v[0][n] * cs + pr * sn);
;                             }
;                         }
.LBB0_490:
	v_lshlrev_b32_e32 v222, 6, v18
	v_and_b32_e32 v222, 0x1ffc0, v222
	global_load_dwordx4 v[206:209], v222, s[40:41] offset:32
	global_load_dwordx4 v[210:213], v222, s[40:41]
	global_load_dwordx4 v[214:217], v222, s[40:41] offset:48
	global_load_dwordx4 v[218:221], v222, s[40:41] offset:16
	v_pk_mul_f32 v[20:21], v[16:17], v[16:17]
	v_pk_mul_f32 v[22:23], v[14:15], v[14:15]
	v_mul_f32_e32 v19, v2, v2
	v_pk_mov_b32 v[24:25], v[22:23], v[20:21] op_sel:[1,0]
	v_mov_b32_e32 v23, v21
	v_pk_add_f32 v[20:21], v[24:25], v[22:23]
	v_pk_mul_f32 v[22:23], v[12:13], v[12:13]
	v_pk_mul_f32 v[24:25], v[10:11], v[10:11]
	v_pk_add_f32 v[20:21], v[20:21], v[20:21] op_sel:[0,1] op_sel_hi:[1,0]
	v_pk_mov_b32 v[26:27], v[24:25], v[22:23] op_sel:[1,0]
	v_mov_b32_e32 v25, v23
	v_pk_add_f32 v[22:23], v[26:27], v[24:25]
	v_mul_f32_e32 v24, v3, v3
	v_pk_add_f32 v[22:23], v[22:23], v[22:23] op_sel:[0,1] op_sel_hi:[1,0]
	v_mov_b32_e32 v21, v19
	v_mov_b32_e32 v23, v24
	v_pk_add_f32 v[20:21], v[20:21], v[22:23]
	v_mul_f32_e32 v22, v7, v7
	v_mul_f32_e32 v25, v4, v4
	v_pk_fma_f32 v[22:23], v[6:7], v[6:7], v[22:23] op_sel_hi:[1,1,0]
	v_mul_f32_e32 v24, v9, v9
	v_mul_f32_e32 v26, v5, v5
	v_mov_b32_e32 v23, v25
	v_pk_fma_f32 v[24:25], v[8:9], v[8:9], v[24:25] op_sel_hi:[1,1,0]
	v_xor_b32_e32 v19, 16, v190
	v_mov_b32_e32 v25, v26
	v_pk_add_f32 v[22:23], v[22:23], v[24:25]
	v_mov_b32_e32 v25, v157
	v_pk_add_f32 v[20:21], v[20:21], v[22:23]
	s_nop 0
	v_add_f32_e32 v20, v20, v21
	v_and_b32_e32 v21, 64, v190
	v_add_u32_e32 v21, 64, v21
	v_cmp_lt_i32_e32 vcc, v19, v21
	s_nop 1
	v_cndmask_b32_e32 v19, v190, v19, vcc
	v_lshlrev_b32_e32 v19, 2, v19
	v_mov_b32_e32 v22, v20
	s_nop 1
	v_permlane16_swap_b32_e32 v22, v20
	v_add_f32_e32 v20, v20, v22
	v_xor_b32_e32 v22, 32, v190
	v_cmp_lt_i32_e32 vcc, v22, v21
	s_nop 1
	v_cndmask_b32_e32 v21, v190, v22, vcc
	v_lshlrev_b32_e32 v21, 2, v21
	v_mov_b32_e32 v21, v20
	s_nop 1
	v_permlane32_swap_b32_e32 v21, v20
	v_add_f32_e32 v20, v20, v21
	v_fmamk_f32 v20, v20, 0x3c800000, v187
	v_rsq_f32_e32 v20, v20
	s_nop 0
	v_pk_mul_f32 v[14:15], v[14:15], v[20:21] op_sel_hi:[1,0]
	v_pk_mul_f32 v[16:17], v[16:17], v[20:21] op_sel_hi:[1,0]
	v_pk_mul_f32 v[14:15], v[142:143], v[14:15]
	v_pk_mul_f32 v[16:17], v[144:145], v[16:17]
	ds_bpermute_b32 v22, v19, v14
	ds_bpermute_b32 v23, v19, v15
	ds_bpermute_b32 v26, v19, v16
	ds_bpermute_b32 v27, v19, v17
	v_lshlrev_b32_e32 v21, 6, v18
	v_and_b32_e32 v24, 0x1ffc0, v21
	v_lshl_add_u64 v[24:25], s[40:41], 0, v[24:25]
	s_and_saveexec_b64 s[10:11], s[4:5]
	s_cbranch_execz .LBB0_492
	s_waitcnt vmcnt(2)
	v_mov_b64_e32 v[28:29], v[206:207]
	v_mov_b64_e32 v[30:31], v[208:209]
	v_mov_b64_e32 v[32:33], v[210:211]
	v_mov_b64_e32 v[34:35], v[212:213]
	s_waitcnt lgkmcnt(0)
	v_pk_mul_f32 v[26:27], v[30:31], v[26:27]
	v_pk_mul_f32 v[22:23], v[28:29], v[22:23]
	v_xor_b32_e32 v21, 0x80000000, v26
	v_xor_b32_e32 v28, 0x80000000, v27
	v_xor_b32_e32 v29, 0x80000000, v22
	v_xor_b32_e32 v30, 0x80000000, v23
	v_cndmask_b32_e64 v27, v27, v28, s[6:7]
	v_cndmask_b32_e64 v26, v26, v21, s[6:7]
	v_cndmask_b32_e64 v23, v23, v30, s[6:7]
	v_cndmask_b32_e64 v22, v22, v29, s[6:7]
	v_pk_fma_f32 v[16:17], v[16:17], v[34:35], v[26:27]
	v_pk_fma_f32 v[14:15], v[14:15], v[32:33], v[22:23]
